# DFTS-Q epilogue load pipelining + GATES epilogue load hoisted above store (counted vmcnt), flat->global in those epilogues
# speedup vs baseline: 1.0118x; 1.0118x over previous
.LBB0_132:
	s_or_b64 exec, exec, s[0:1]
	v_add_u32_e32 v207, 0x90, v206
	v_add_u32_e32 v186, s16, v207
	v_ashrrev_i32_e32 v187, 31, v186
	v_lshlrev_b64 v[188:189], 12, v[186:187]
	v_lshl_add_u64 v[188:189], s[26:27], 0, v[188:189]
	v_lshl_add_u64 v[188:189], v[188:189], 0, v[198:199]
	flat_load_dwordx4 v[190:193], v[188:189] nt
	v_add_u32_e32 v186, s16, v186
	s_mov_b32 s0, 0x3c800000
	s_waitcnt vmcnt(0) lgkmcnt(0)
	v_pk_add_f32 v[192:193], v[200:201], v[192:193]
	s_nop 0
	v_sub_f32_e32 v187, v192, v54
	v_pk_add_f32 v[194:195], v[204:205], v[190:191]
	v_sub_f32_e32 v190, v193, v55
	v_cvt_pk_bf16_f32 v197, v187, v190
	v_ashrrev_i32_e32 v187, 31, v186
	v_lshlrev_b64 v[186:187], 11, v[186:187]
	v_sub_f32_e32 v191, v194, v52
	v_sub_f32_e32 v196, v195, v53
	v_lshl_add_u64 v[186:187], s[24:25], 0, v[186:187]
	v_cvt_pk_bf16_f32 v196, v191, v196
	v_lshl_add_u64 v[190:191], v[186:187], 0, v[202:203]
	v_pk_add_f32 v[186:187], v[54:55], v[192:193]
	v_pk_add_f32 v[192:193], v[52:53], v[194:195]
	flat_store_dwordx2 v[190:191], v[196:197]
	v_cvt_pk_bf16_f32 v192, v192, v193
	v_cvt_pk_bf16_f32 v193, v186, v187
	v_sub_u32_e32 v186, s15, v207
	v_ashrrev_i32_e32 v187, 31, v186
	v_lshlrev_b64 v[186:187], 11, v[186:187]
	v_add_u32_e32 v207, 0xa0, v206
	v_lshl_add_u64 v[186:187], s[24:25], 0, v[186:187]
	v_add_u32_e32 v208, s16, v207
	v_lshl_add_u64 v[186:187], v[186:187], 0, v[202:203]
	v_ashrrev_i32_e32 v209, 31, v208
	flat_store_dwordx2 v[186:187], v[192:193]
	v_lshlrev_b64 v[192:193], 12, v[208:209]
	v_lshl_add_u64 v[192:193], s[26:27], 0, v[192:193]
	v_lshl_add_u64 v[192:193], v[192:193], 0, v[198:199]
	flat_load_dwordx4 v[194:197], v[192:193] nt
	s_waitcnt vmcnt(0) lgkmcnt(0)
	v_pk_add_f32 v[210:211], v[200:201], v[196:197]
	v_pk_add_f32 v[194:195], v[204:205], v[194:195]
	v_sub_f32_e32 v196, v210, v38
	v_sub_f32_e32 v209, v194, v36
	v_sub_f32_e32 v241, v195, v37
	v_pk_add_f32 v[194:195], v[36:37], v[194:195]
	v_sub_f32_e32 v197, v211, v39
	v_cvt_pk_bf16_f32 v242, v209, v241
	v_cvt_pk_bf16_f32 v243, v196, v197
	v_add_u32_e32 v196, s16, v208
	v_pk_add_f32 v[208:209], v[38:39], v[210:211]
	v_cvt_pk_bf16_f32 v210, v194, v195
	v_sub_u32_e32 v194, s15, v207
	v_ashrrev_i32_e32 v197, 31, v196
	v_ashrrev_i32_e32 v195, 31, v194
	v_lshlrev_b64 v[196:197], 11, v[196:197]
	v_lshlrev_b64 v[194:195], 11, v[194:195]
	v_lshl_add_u64 v[196:197], s[24:25], 0, v[196:197]
	v_lshl_add_u64 v[194:195], s[24:25], 0, v[194:195]
	v_lshl_add_u64 v[196:197], v[196:197], 0, v[202:203]
	v_lshl_add_u64 v[194:195], v[194:195], 0, v[202:203]
	v_add_u32_e32 v241, 0xb0, v206
	flat_store_dwordx2 v[196:197], v[242:243]
	v_cvt_pk_bf16_f32 v211, v208, v209
	flat_store_dwordx2 v[194:195], v[210:211]
	v_add_u32_e32 v210, s16, v241
	v_ashrrev_i32_e32 v211, 31, v210
	v_lshlrev_b64 v[206:207], 12, v[210:211]
	v_lshl_add_u64 v[206:207], s[26:27], 0, v[206:207]
	v_lshl_add_u64 v[198:199], v[206:207], 0, v[198:199]
	flat_load_dwordx4 v[206:209], v[198:199] nt
	s_waitcnt vmcnt(0) lgkmcnt(0)
	v_pk_add_f32 v[208:209], v[200:201], v[208:209]
	v_pk_add_f32 v[204:205], v[204:205], v[206:207]
	v_sub_f32_e32 v200, v208, v22
	v_sub_f32_e32 v206, v204, v20
	v_sub_f32_e32 v207, v205, v21
	v_sub_f32_e32 v201, v209, v23
	v_cvt_pk_bf16_f32 v206, v206, v207
	v_cvt_pk_bf16_f32 v207, v200, v201
	v_add_u32_e32 v200, s16, v210
	v_ashrrev_i32_e32 v201, 31, v200
	v_lshlrev_b64 v[200:201], 11, v[200:201]
	v_lshl_add_u64 v[200:201], s[24:25], 0, v[200:201]
	v_lshl_add_u64 v[200:201], v[200:201], 0, v[202:203]
	flat_store_dwordx2 v[200:201], v[206:207]
	v_pk_add_f32 v[206:207], v[22:23], v[208:209]
	v_pk_add_f32 v[204:205], v[20:21], v[204:205]
	s_nop 0
	v_cvt_pk_bf16_f32 v204, v204, v205
	v_cvt_pk_bf16_f32 v205, v206, v207
	v_sub_u32_e32 v206, s15, v241
	v_ashrrev_i32_e32 v207, 31, v206
	v_lshlrev_b64 v[206:207], 11, v[206:207]
	v_lshl_add_u64 v[206:207], s[24:25], 0, v[206:207]
	v_lshl_add_u64 v[202:203], v[206:207], 0, v[202:203]
	flat_store_dwordx2 v[202:203], v[204:205]
	global_load_dwordx4 v[204:207], v[160:161], off offset:64
	global_load_dwordx4 v[242:245], v[158:159], off offset:64 nt
	s_waitcnt vmcnt(0) lgkmcnt(0)
	global_load_dwordx4 v[232:235], v[162:163], off offset:64 nt
	global_load_dwordx4 v[246:249], v[168:169], off offset:64 nt
	v_pk_mul_f32 v[206:207], v[206:207], s[0:1] op_sel_hi:[1,0]
	v_pk_mul_f32 v[208:209], v[204:205], s[0:1] op_sel_hi:[1,0]
	v_xor_b32_e32 v204, 0x80000000, v206
	v_xor_b32_e32 v205, 0x80000000, v207
	v_xor_b32_e32 v210, 0x80000000, v208
	v_xor_b32_e32 v211, 0x80000000, v209
	v_cndmask_b32_e64 v205, v205, v207, s[8:9]
	v_cndmask_b32_e64 v204, v204, v206, s[8:9]
	v_cndmask_b32_e64 v207, v211, v209, s[8:9]
	v_cndmask_b32_e64 v206, v210, v208, s[8:9]
	v_pk_add_f32 v[208:209], v[244:245], v[204:205]
	v_pk_add_f32 v[210:211], v[242:243], v[206:207]
	v_sub_f32_e32 v243, v209, v123
	v_sub_f32_e32 v242, v210, v120
	v_sub_f32_e32 v241, v208, v122
	v_sub_f32_e32 v244, v211, v121
	v_cvt_pk_bf16_f32 v242, v242, v244
	v_cvt_pk_bf16_f32 v243, v241, v243
	global_store_dwordx2 v[156:157], v[242:243], off offset:32
	s_and_saveexec_b64 s[0:1], vcc
	s_cbranch_execz .LBB0_134
	v_pk_add_f32 v[208:209], v[122:123], v[208:209]
	v_pk_add_f32 v[210:211], v[120:121], v[210:211]
	s_nop 0
	v_cvt_pk_bf16_f32 v210, v210, v211
	v_cvt_pk_bf16_f32 v211, v208, v209
	v_lshlrev_b64 v[208:209], 11, v[154:155]
	v_lshl_add_u64 v[208:209], s[24:25], 0, v[208:209]
	v_lshl_add_u64 v[208:209], v[138:139], 1, v[208:209]
	global_store_dwordx2 v[208:209], v[210:211], off offset:32
.LBB0_134:
	s_or_b64 exec, exec, s[0:1]
	s_waitcnt vmcnt(3)
	v_mov_b64_e32 v[208:209], v[232:233]
	v_mov_b64_e32 v[210:211], v[234:235]
	global_load_dwordx4 v[228:231], v[174:175], off offset:64 nt
	v_pk_add_f32 v[210:211], v[204:205], v[210:211]
	v_pk_add_f32 v[208:209], v[206:207], v[208:209]
	v_sub_f32_e32 v243, v211, v115
	v_sub_f32_e32 v242, v208, v112
	v_sub_f32_e32 v244, v209, v113
	v_pk_add_f32 v[208:209], v[112:113], v[208:209]
	v_sub_f32_e32 v241, v210, v114
	v_cvt_pk_bf16_f32 v242, v242, v244
	v_cvt_pk_bf16_f32 v243, v241, v243
	global_store_dwordx2 v[166:167], v[242:243], off offset:32
	v_pk_add_f32 v[210:211], v[114:115], v[210:211]
	v_cvt_pk_bf16_f32 v208, v208, v209
	s_nop 0
	v_cvt_pk_bf16_f32 v209, v210, v211
	global_store_dwordx2 v[164:165], v[208:209], off offset:32
	s_waitcnt vmcnt(5)
	v_mov_b64_e32 v[208:209], v[246:247]
	v_mov_b64_e32 v[210:211], v[248:249]
	global_load_dwordx4 v[232:235], v[180:181], off offset:64 nt
	v_pk_add_f32 v[210:211], v[204:205], v[210:211]
	v_pk_add_f32 v[208:209], v[206:207], v[208:209]
	v_sub_f32_e32 v243, v211, v99
	v_sub_f32_e32 v242, v208, v96
	v_sub_f32_e32 v244, v209, v97
	v_pk_add_f32 v[208:209], v[96:97], v[208:209]
	v_sub_f32_e32 v241, v210, v98
	v_cvt_pk_bf16_f32 v242, v242, v244
	v_cvt_pk_bf16_f32 v243, v241, v243
	global_store_dwordx2 v[172:173], v[242:243], off offset:32
	v_pk_add_f32 v[210:211], v[98:99], v[210:211]
	v_cvt_pk_bf16_f32 v208, v208, v209
	s_nop 0
	v_cvt_pk_bf16_f32 v209, v210, v211
	global_store_dwordx2 v[170:171], v[208:209], off offset:32
	s_waitcnt vmcnt(5)
	v_mov_b64_e32 v[208:209], v[228:229]
	v_mov_b64_e32 v[210:211], v[230:231]
	global_load_dwordx4 v[246:249], v[188:189], off offset:64 nt
	v_pk_add_f32 v[210:211], v[204:205], v[210:211]
	v_pk_add_f32 v[208:209], v[206:207], v[208:209]
	v_sub_f32_e32 v243, v211, v83
	v_sub_f32_e32 v242, v208, v80
	v_sub_f32_e32 v244, v209, v81
	v_pk_add_f32 v[208:209], v[80:81], v[208:209]
	v_sub_f32_e32 v241, v210, v82
	v_cvt_pk_bf16_f32 v242, v242, v244
	v_cvt_pk_bf16_f32 v243, v241, v243
	global_store_dwordx2 v[178:179], v[242:243], off offset:32
	v_pk_add_f32 v[210:211], v[82:83], v[210:211]
	v_cvt_pk_bf16_f32 v208, v208, v209
	s_nop 0
	v_cvt_pk_bf16_f32 v209, v210, v211
	global_store_dwordx2 v[176:177], v[208:209], off offset:32
	s_waitcnt vmcnt(5)
	v_mov_b64_e32 v[242:243], v[232:233]
	v_mov_b64_e32 v[244:245], v[234:235]
	global_load_dwordx4 v[228:231], v[192:193], off offset:64 nt
	v_pk_add_f32 v[208:209], v[204:205], v[244:245]
	v_pk_add_f32 v[210:211], v[206:207], v[242:243]
	v_sub_f32_e32 v243, v209, v59
	v_sub_f32_e32 v242, v210, v56
	v_sub_f32_e32 v241, v208, v58
	v_sub_f32_e32 v244, v211, v57
	v_cvt_pk_bf16_f32 v242, v242, v244
	v_cvt_pk_bf16_f32 v243, v241, v243
	global_store_dwordx2 v[182:183], v[242:243], off offset:32
	s_and_saveexec_b64 s[0:1], s[10:11]
	s_cbranch_execz .LBB0_136
	v_pk_add_f32 v[208:209], v[58:59], v[208:209]
	v_pk_add_f32 v[210:211], v[56:57], v[210:211]
	s_nop 0
	v_cvt_pk_bf16_f32 v210, v210, v211
	v_cvt_pk_bf16_f32 v211, v208, v209
	v_lshlrev_b64 v[208:209], 11, v[184:185]
	v_lshl_add_u64 v[208:209], s[24:25], 0, v[208:209]
	v_lshl_add_u64 v[208:209], v[138:139], 1, v[208:209]
	global_store_dwordx2 v[208:209], v[210:211], off offset:32
.LBB0_136:
	s_or_b64 exec, exec, s[0:1]
	s_waitcnt vmcnt(5)
	v_mov_b64_e32 v[208:209], v[246:247]
	v_mov_b64_e32 v[210:211], v[248:249]
	global_load_dwordx4 v[232:235], v[198:199], off offset:64 nt
	s_mov_b32 s0, 0x3c800000
	v_pk_add_f32 v[210:211], v[204:205], v[210:211]
	v_pk_add_f32 v[208:209], v[206:207], v[208:209]
	v_sub_f32_e32 v243, v211, v51
	v_sub_f32_e32 v242, v208, v48
	v_sub_f32_e32 v244, v209, v49
	v_pk_add_f32 v[208:209], v[48:49], v[208:209]
	v_sub_f32_e32 v241, v210, v50
	v_cvt_pk_bf16_f32 v242, v242, v244
	v_cvt_pk_bf16_f32 v243, v241, v243
	global_store_dwordx2 v[190:191], v[242:243], off offset:32
	v_pk_add_f32 v[210:211], v[50:51], v[210:211]
	v_cvt_pk_bf16_f32 v208, v208, v209
	s_nop 0
	v_cvt_pk_bf16_f32 v209, v210, v211
	global_store_dwordx2 v[186:187], v[208:209], off offset:32
	s_waitcnt vmcnt(5)
	v_mov_b64_e32 v[208:209], v[228:229]
	v_mov_b64_e32 v[210:211], v[230:231]
	v_pk_add_f32 v[210:211], v[204:205], v[210:211]
	v_pk_add_f32 v[208:209], v[206:207], v[208:209]
	v_sub_f32_e32 v243, v211, v35
	v_sub_f32_e32 v242, v208, v32
	v_sub_f32_e32 v244, v209, v33
	v_pk_add_f32 v[208:209], v[32:33], v[208:209]
	v_sub_f32_e32 v241, v210, v34
	v_cvt_pk_bf16_f32 v242, v242, v244
	v_cvt_pk_bf16_f32 v243, v241, v243
	global_store_dwordx2 v[196:197], v[242:243], off offset:32
	v_pk_add_f32 v[210:211], v[34:35], v[210:211]
	v_cvt_pk_bf16_f32 v208, v208, v209
	s_nop 0
	v_cvt_pk_bf16_f32 v209, v210, v211
	global_store_dwordx2 v[194:195], v[208:209], off offset:32
	s_waitcnt vmcnt(4)
	v_mov_b64_e32 v[208:209], v[232:233]
	v_mov_b64_e32 v[210:211], v[234:235]
	v_pk_add_f32 v[204:205], v[204:205], v[210:211]
	v_pk_add_f32 v[206:207], v[206:207], v[208:209]
	v_sub_f32_e32 v209, v204, v18
	v_sub_f32_e32 v208, v206, v16
	v_sub_f32_e32 v211, v207, v17
	v_pk_add_f32 v[206:207], v[16:17], v[206:207]
	v_sub_f32_e32 v210, v205, v19
	v_cvt_pk_bf16_f32 v208, v208, v211
	v_cvt_pk_bf16_f32 v209, v209, v210
	global_store_dwordx2 v[200:201], v[208:209], off offset:32
	v_pk_add_f32 v[204:205], v[18:19], v[204:205]
	v_cvt_pk_bf16_f32 v206, v206, v207
	s_nop 0
	v_cvt_pk_bf16_f32 v207, v204, v205
	global_store_dwordx2 v[202:203], v[206:207], off offset:32
	global_load_dwordx4 v[204:207], v[160:161], off offset:512
	global_load_dwordx4 v[242:245], v[158:159], off offset:512 nt
	s_waitcnt vmcnt(0) lgkmcnt(0)
	global_load_dwordx4 v[232:235], v[162:163], off offset:512 nt
	global_load_dwordx4 v[246:249], v[168:169], off offset:512 nt
	v_pk_mul_f32 v[206:207], v[206:207], s[0:1] op_sel_hi:[1,0]
	v_pk_mul_f32 v[208:209], v[204:205], s[0:1] op_sel_hi:[1,0]
	v_xor_b32_e32 v204, 0x80000000, v206
	v_xor_b32_e32 v205, 0x80000000, v207
	v_xor_b32_e32 v210, 0x80000000, v208
	v_xor_b32_e32 v211, 0x80000000, v209
	v_cndmask_b32_e64 v205, v205, v207, s[8:9]
	v_cndmask_b32_e64 v204, v204, v206, s[8:9]
	v_cndmask_b32_e64 v207, v211, v209, s[8:9]
	v_cndmask_b32_e64 v206, v210, v208, s[8:9]
	v_pk_add_f32 v[208:209], v[244:245], v[204:205]
	v_pk_add_f32 v[210:211], v[242:243], v[206:207]
	v_sub_f32_e32 v243, v209, v111
	v_sub_f32_e32 v242, v210, v108
	v_sub_f32_e32 v241, v208, v110
	v_sub_f32_e32 v244, v211, v109
	v_cvt_pk_bf16_f32 v242, v242, v244
	v_cvt_pk_bf16_f32 v243, v241, v243
	global_store_dwordx2 v[156:157], v[242:243], off offset:256
	s_and_saveexec_b64 s[0:1], vcc
	s_cbranch_execz .LBB0_138
	v_pk_add_f32 v[208:209], v[110:111], v[208:209]
	v_pk_add_f32 v[210:211], v[108:109], v[210:211]
	s_nop 0
	v_cvt_pk_bf16_f32 v210, v210, v211
	v_cvt_pk_bf16_f32 v211, v208, v209
	v_lshlrev_b64 v[208:209], 11, v[154:155]
	v_lshl_add_u64 v[208:209], s[24:25], 0, v[208:209]
	v_lshl_add_u64 v[208:209], v[138:139], 1, v[208:209]
	global_store_dwordx2 v[208:209], v[210:211], off offset:256
.LBB0_138:
	s_or_b64 exec, exec, s[0:1]
	s_waitcnt vmcnt(3)
	v_mov_b64_e32 v[208:209], v[232:233]
	v_mov_b64_e32 v[210:211], v[234:235]
	global_load_dwordx4 v[228:231], v[174:175], off offset:512 nt
	v_pk_add_f32 v[210:211], v[204:205], v[210:211]
	v_pk_add_f32 v[208:209], v[206:207], v[208:209]
	v_sub_f32_e32 v243, v211, v95
	v_sub_f32_e32 v242, v208, v92
	v_sub_f32_e32 v244, v209, v93
	v_pk_add_f32 v[208:209], v[92:93], v[208:209]
	v_sub_f32_e32 v241, v210, v94
	v_cvt_pk_bf16_f32 v242, v242, v244
	v_cvt_pk_bf16_f32 v243, v241, v243
	global_store_dwordx2 v[166:167], v[242:243], off offset:256
	v_pk_add_f32 v[210:211], v[94:95], v[210:211]
	v_cvt_pk_bf16_f32 v208, v208, v209
	s_nop 0
	v_cvt_pk_bf16_f32 v209, v210, v211
	global_store_dwordx2 v[164:165], v[208:209], off offset:256
	s_waitcnt vmcnt(5)
	v_mov_b64_e32 v[208:209], v[246:247]
	v_mov_b64_e32 v[210:211], v[248:249]
	global_load_dwordx4 v[232:235], v[180:181], off offset:512 nt
	v_pk_add_f32 v[210:211], v[204:205], v[210:211]
	v_pk_add_f32 v[208:209], v[206:207], v[208:209]
	v_sub_f32_e32 v243, v211, v79
	v_sub_f32_e32 v242, v208, v76
	v_sub_f32_e32 v244, v209, v77
	v_pk_add_f32 v[208:209], v[76:77], v[208:209]
	v_sub_f32_e32 v241, v210, v78
	v_cvt_pk_bf16_f32 v242, v242, v244
	v_cvt_pk_bf16_f32 v243, v241, v243
	global_store_dwordx2 v[172:173], v[242:243], off offset:256
	v_pk_add_f32 v[210:211], v[78:79], v[210:211]
	v_cvt_pk_bf16_f32 v208, v208, v209
	s_nop 0
	v_cvt_pk_bf16_f32 v209, v210, v211
	global_store_dwordx2 v[170:171], v[208:209], off offset:256
	s_waitcnt vmcnt(5)
	v_mov_b64_e32 v[208:209], v[228:229]
	v_mov_b64_e32 v[210:211], v[230:231]
	global_load_dwordx4 v[246:249], v[188:189], off offset:512 nt
	v_pk_add_f32 v[210:211], v[204:205], v[210:211]
	v_pk_add_f32 v[208:209], v[206:207], v[208:209]
	v_sub_f32_e32 v243, v211, v71
	v_sub_f32_e32 v242, v208, v68
	v_sub_f32_e32 v244, v209, v69
	v_pk_add_f32 v[208:209], v[68:69], v[208:209]
	v_sub_f32_e32 v241, v210, v70
	v_cvt_pk_bf16_f32 v242, v242, v244
	v_cvt_pk_bf16_f32 v243, v241, v243
	global_store_dwordx2 v[178:179], v[242:243], off offset:256
	v_pk_add_f32 v[210:211], v[70:71], v[210:211]
	v_cvt_pk_bf16_f32 v208, v208, v209
	s_nop 0
	v_cvt_pk_bf16_f32 v209, v210, v211
	global_store_dwordx2 v[176:177], v[208:209], off offset:256
	s_waitcnt vmcnt(5)
	v_mov_b64_e32 v[242:243], v[232:233]
	v_mov_b64_e32 v[244:245], v[234:235]
	global_load_dwordx4 v[228:231], v[192:193], off offset:512 nt
	v_pk_add_f32 v[208:209], v[204:205], v[244:245]
	v_pk_add_f32 v[210:211], v[206:207], v[242:243]
	v_sub_f32_e32 v243, v209, v47
	v_sub_f32_e32 v242, v210, v44
	v_sub_f32_e32 v241, v208, v46
	v_sub_f32_e32 v244, v211, v45
	v_cvt_pk_bf16_f32 v242, v242, v244
	v_cvt_pk_bf16_f32 v243, v241, v243
	global_store_dwordx2 v[182:183], v[242:243], off offset:256
	s_and_saveexec_b64 s[0:1], s[10:11]
	s_cbranch_execz .LBB0_140
	v_pk_add_f32 v[208:209], v[46:47], v[208:209]
	v_pk_add_f32 v[210:211], v[44:45], v[210:211]
	s_nop 0
	v_cvt_pk_bf16_f32 v210, v210, v211
	v_cvt_pk_bf16_f32 v211, v208, v209
	v_lshlrev_b64 v[208:209], 11, v[184:185]
	v_lshl_add_u64 v[208:209], s[24:25], 0, v[208:209]
	v_lshl_add_u64 v[208:209], v[138:139], 1, v[208:209]
	global_store_dwordx2 v[208:209], v[210:211], off offset:256
.LBB0_140:
	s_or_b64 exec, exec, s[0:1]
	s_waitcnt vmcnt(5)
	v_mov_b64_e32 v[208:209], v[246:247]
	v_mov_b64_e32 v[210:211], v[248:249]
	global_load_dwordx4 v[232:235], v[198:199], off offset:512 nt
	s_mov_b32 s0, 0x3c800000
	v_pk_add_f32 v[210:211], v[204:205], v[210:211]
	v_pk_add_f32 v[208:209], v[206:207], v[208:209]
	v_sub_f32_e32 v243, v211, v31
	v_sub_f32_e32 v242, v208, v28
	v_sub_f32_e32 v244, v209, v29
	v_pk_add_f32 v[208:209], v[28:29], v[208:209]
	v_sub_f32_e32 v241, v210, v30
	v_cvt_pk_bf16_f32 v242, v242, v244
	v_cvt_pk_bf16_f32 v243, v241, v243
	global_store_dwordx2 v[190:191], v[242:243], off offset:256
	v_pk_add_f32 v[210:211], v[30:31], v[210:211]
	v_cvt_pk_bf16_f32 v208, v208, v209
	s_nop 0
	v_cvt_pk_bf16_f32 v209, v210, v211
	global_store_dwordx2 v[186:187], v[208:209], off offset:256
	s_waitcnt vmcnt(5)
	v_mov_b64_e32 v[208:209], v[228:229]
	v_mov_b64_e32 v[210:211], v[230:231]
	v_pk_add_f32 v[210:211], v[204:205], v[210:211]
	v_pk_add_f32 v[208:209], v[206:207], v[208:209]
	v_sub_f32_e32 v243, v211, v15
	v_sub_f32_e32 v242, v208, v12
	v_sub_f32_e32 v244, v209, v13
	v_pk_add_f32 v[208:209], v[12:13], v[208:209]
	v_sub_f32_e32 v241, v210, v14
	v_cvt_pk_bf16_f32 v242, v242, v244
	v_cvt_pk_bf16_f32 v243, v241, v243
	global_store_dwordx2 v[196:197], v[242:243], off offset:256
	v_pk_add_f32 v[210:211], v[14:15], v[210:211]
	v_cvt_pk_bf16_f32 v208, v208, v209
	s_nop 0
	v_cvt_pk_bf16_f32 v209, v210, v211
	global_store_dwordx2 v[194:195], v[208:209], off offset:256
	s_waitcnt vmcnt(4)
	v_mov_b64_e32 v[208:209], v[232:233]
	v_mov_b64_e32 v[210:211], v[234:235]
	v_pk_add_f32 v[204:205], v[204:205], v[210:211]
	v_pk_add_f32 v[206:207], v[206:207], v[208:209]
	v_sub_f32_e32 v209, v204, v6
	v_sub_f32_e32 v208, v206, v4
	v_sub_f32_e32 v211, v207, v5
	v_pk_add_f32 v[206:207], v[4:5], v[206:207]
	v_sub_f32_e32 v210, v205, v7
	v_cvt_pk_bf16_f32 v208, v208, v211
	v_cvt_pk_bf16_f32 v209, v209, v210
	global_store_dwordx2 v[200:201], v[208:209], off offset:256
	v_pk_add_f32 v[204:205], v[6:7], v[204:205]
	v_cvt_pk_bf16_f32 v206, v206, v207
	s_nop 0
	v_cvt_pk_bf16_f32 v207, v204, v205
	global_store_dwordx2 v[202:203], v[206:207], off offset:256
	global_load_dwordx4 v[204:207], v[160:161], off offset:576
	s_waitcnt vmcnt(0) lgkmcnt(0)
	v_pk_mul_f32 v[160:161], v[206:207], s[0:1] op_sel_hi:[1,0]
	v_pk_mul_f32 v[204:205], v[204:205], s[0:1] op_sel_hi:[1,0]
	v_xor_b32_e32 v206, 0x80000000, v160
	v_xor_b32_e32 v207, 0x80000000, v161
	v_xor_b32_e32 v208, 0x80000000, v204
	v_xor_b32_e32 v209, 0x80000000, v205
	v_cndmask_b32_e64 v161, v207, v161, s[8:9]
	v_cndmask_b32_e64 v160, v206, v160, s[8:9]
	v_cndmask_b32_e64 v205, v209, v205, s[8:9]
	v_cndmask_b32_e64 v204, v208, v204, s[8:9]
	global_load_dwordx4 v[206:209], v[158:159], off offset:576 nt
	s_waitcnt vmcnt(0) lgkmcnt(0)
	global_load_dwordx4 v[232:235], v[162:163], off offset:576 nt
	global_load_dwordx4 v[246:249], v[168:169], off offset:576 nt
	v_pk_add_f32 v[158:159], v[208:209], v[160:161]
	v_pk_add_f32 v[206:207], v[206:207], v[204:205]
	v_sub_f32_e32 v209, v158, v102
	v_sub_f32_e32 v208, v206, v100
	v_sub_f32_e32 v210, v159, v103
	v_sub_f32_e32 v211, v207, v101
	v_cvt_pk_bf16_f32 v208, v208, v211
	v_cvt_pk_bf16_f32 v209, v209, v210
	global_store_dwordx2 v[156:157], v[208:209], off offset:288
	s_and_saveexec_b64 s[0:1], vcc
	s_cbranch_execz .LBB0_142
	v_lshlrev_b64 v[154:155], 11, v[154:155]
	v_lshl_add_u64 v[154:155], s[24:25], 0, v[154:155]
	v_pk_add_f32 v[156:157], v[102:103], v[158:159]
	v_pk_add_f32 v[158:159], v[100:101], v[206:207]
	v_lshl_add_u64 v[154:155], v[138:139], 1, v[154:155]
	v_cvt_pk_bf16_f32 v158, v158, v159
	v_cvt_pk_bf16_f32 v159, v156, v157
	global_store_dwordx2 v[154:155], v[158:159], off offset:288
.LBB0_142:
	s_or_b64 exec, exec, s[0:1]
	s_waitcnt vmcnt(3)
	v_mov_b64_e32 v[154:155], v[232:233]
	v_mov_b64_e32 v[156:157], v[234:235]
	global_load_dwordx4 v[228:231], v[174:175], off offset:576 nt
	v_pk_add_f32 v[156:157], v[160:161], v[156:157]
	v_pk_add_f32 v[154:155], v[204:205], v[154:155]
	v_sub_f32_e32 v159, v156, v86
	v_sub_f32_e32 v158, v154, v84
	v_sub_f32_e32 v163, v155, v85
	v_pk_add_f32 v[154:155], v[84:85], v[154:155]
	v_sub_f32_e32 v162, v157, v87
	v_cvt_pk_bf16_f32 v158, v158, v163
	v_cvt_pk_bf16_f32 v159, v159, v162
	global_store_dwordx2 v[166:167], v[158:159], off offset:288
	v_pk_add_f32 v[156:157], v[86:87], v[156:157]
	v_cvt_pk_bf16_f32 v154, v154, v155
	s_nop 0
	v_cvt_pk_bf16_f32 v155, v156, v157
	global_store_dwordx2 v[164:165], v[154:155], off offset:288
	s_waitcnt vmcnt(5)
	v_mov_b64_e32 v[154:155], v[246:247]
	v_mov_b64_e32 v[156:157], v[248:249]
	global_load_dwordx4 v[232:235], v[180:181], off offset:576 nt
	v_pk_add_f32 v[156:157], v[160:161], v[156:157]
	v_pk_add_f32 v[154:155], v[204:205], v[154:155]
	v_sub_f32_e32 v159, v156, v74
	v_sub_f32_e32 v158, v154, v72
	v_sub_f32_e32 v163, v155, v73
	v_pk_add_f32 v[154:155], v[72:73], v[154:155]
	v_sub_f32_e32 v162, v157, v75
	v_cvt_pk_bf16_f32 v158, v158, v163
	v_cvt_pk_bf16_f32 v159, v159, v162
	global_store_dwordx2 v[172:173], v[158:159], off offset:288
	v_pk_add_f32 v[156:157], v[74:75], v[156:157]
	v_cvt_pk_bf16_f32 v154, v154, v155
	s_nop 0
	v_cvt_pk_bf16_f32 v155, v156, v157
	global_store_dwordx2 v[170:171], v[154:155], off offset:288
	s_waitcnt vmcnt(5)
	v_mov_b64_e32 v[154:155], v[228:229]
	v_mov_b64_e32 v[156:157], v[230:231]
	global_load_dwordx4 v[246:249], v[188:189], off offset:576 nt
	v_pk_add_f32 v[156:157], v[160:161], v[156:157]
	v_pk_add_f32 v[154:155], v[204:205], v[154:155]
	v_sub_f32_e32 v159, v156, v66
	v_sub_f32_e32 v158, v154, v64
	v_sub_f32_e32 v163, v155, v65
	v_pk_add_f32 v[154:155], v[64:65], v[154:155]
	v_sub_f32_e32 v162, v157, v67
	v_cvt_pk_bf16_f32 v158, v158, v163
	v_cvt_pk_bf16_f32 v159, v159, v162
	global_store_dwordx2 v[178:179], v[158:159], off offset:288
	v_pk_add_f32 v[156:157], v[66:67], v[156:157]
	v_cvt_pk_bf16_f32 v154, v154, v155
	s_nop 0
	v_cvt_pk_bf16_f32 v155, v156, v157
	global_store_dwordx2 v[176:177], v[154:155], off offset:288
	s_waitcnt vmcnt(5)
	v_mov_b64_e32 v[156:157], v[232:233]
	v_mov_b64_e32 v[158:159], v[234:235]
	global_load_dwordx4 v[228:231], v[192:193], off offset:576 nt
	v_pk_add_f32 v[154:155], v[160:161], v[158:159]
	v_pk_add_f32 v[156:157], v[204:205], v[156:157]
	v_sub_f32_e32 v159, v154, v42
	v_sub_f32_e32 v158, v156, v40
	v_sub_f32_e32 v162, v155, v43
	v_sub_f32_e32 v163, v157, v41
	v_cvt_pk_bf16_f32 v158, v158, v163
	v_cvt_pk_bf16_f32 v159, v159, v162
	global_store_dwordx2 v[182:183], v[158:159], off offset:288
	s_and_saveexec_b64 s[0:1], s[10:11]
	s_cbranch_execz .LBB0_144
	v_pk_add_f32 v[154:155], v[42:43], v[154:155]
	v_pk_add_f32 v[156:157], v[40:41], v[156:157]
	s_nop 0
	v_cvt_pk_bf16_f32 v156, v156, v157
	v_cvt_pk_bf16_f32 v157, v154, v155
	v_lshlrev_b64 v[154:155], 11, v[184:185]
	v_lshl_add_u64 v[154:155], s[24:25], 0, v[154:155]
	v_lshl_add_u64 v[154:155], v[138:139], 1, v[154:155]
	global_store_dwordx2 v[154:155], v[156:157], off offset:288
.LBB0_144:
	s_or_b64 exec, exec, s[0:1]
	s_waitcnt vmcnt(5)
	v_mov_b64_e32 v[154:155], v[246:247]
	v_mov_b64_e32 v[156:157], v[248:249]
	global_load_dwordx4 v[232:235], v[198:199], off offset:576 nt
	s_mov_b64 s[0:1], 0
	v_pk_add_f32 v[156:157], v[160:161], v[156:157]
	v_pk_add_f32 v[154:155], v[204:205], v[154:155]
	v_sub_f32_e32 v159, v156, v26
	v_sub_f32_e32 v158, v154, v24
	v_sub_f32_e32 v163, v155, v25
	v_pk_add_f32 v[154:155], v[24:25], v[154:155]
	v_sub_f32_e32 v162, v157, v27
	v_cvt_pk_bf16_f32 v158, v158, v163
	v_cvt_pk_bf16_f32 v159, v159, v162
	global_store_dwordx2 v[190:191], v[158:159], off offset:288
	v_pk_add_f32 v[156:157], v[26:27], v[156:157]
	v_cvt_pk_bf16_f32 v154, v154, v155
	s_nop 0
	v_cvt_pk_bf16_f32 v155, v156, v157
	global_store_dwordx2 v[186:187], v[154:155], off offset:288
	s_waitcnt vmcnt(5)
	v_mov_b64_e32 v[154:155], v[228:229]
	v_mov_b64_e32 v[156:157], v[230:231]
	v_pk_add_f32 v[156:157], v[160:161], v[156:157]
	v_pk_add_f32 v[154:155], v[204:205], v[154:155]
	v_sub_f32_e32 v159, v156, v10
	v_sub_f32_e32 v158, v154, v8
	v_sub_f32_e32 v163, v155, v9
	v_pk_add_f32 v[154:155], v[8:9], v[154:155]
	v_sub_f32_e32 v162, v157, v11
	v_cvt_pk_bf16_f32 v158, v158, v163
	v_cvt_pk_bf16_f32 v159, v159, v162
	global_store_dwordx2 v[196:197], v[158:159], off offset:288
	v_pk_add_f32 v[156:157], v[10:11], v[156:157]
	v_cvt_pk_bf16_f32 v154, v154, v155
	s_nop 0
	v_cvt_pk_bf16_f32 v155, v156, v157
	global_store_dwordx2 v[194:195], v[154:155], off offset:288
	s_waitcnt vmcnt(4)
	v_mov_b64_e32 v[154:155], v[232:233]
	v_mov_b64_e32 v[156:157], v[234:235]
	v_pk_add_f32 v[156:157], v[160:161], v[156:157]
	v_pk_add_f32 v[154:155], v[204:205], v[154:155]
	v_sub_f32_e32 v159, v156, v2
	v_sub_f32_e32 v158, v154, v0
	v_sub_f32_e32 v161, v155, v1
	v_pk_add_f32 v[154:155], v[0:1], v[154:155]
	v_sub_f32_e32 v160, v157, v3
	v_cvt_pk_bf16_f32 v158, v158, v161
	v_cvt_pk_bf16_f32 v159, v159, v160
	global_store_dwordx2 v[200:201], v[158:159], off offset:288
	v_pk_add_f32 v[156:157], v[2:3], v[156:157]
	v_cvt_pk_bf16_f32 v154, v154, v155
	s_nop 0
	v_cvt_pk_bf16_f32 v155, v156, v157
	global_store_dwordx2 v[202:203], v[154:155], off offset:288

.LBB0_392:
	v_mbcnt_lo_u32_b32 v128, -1, 0
	v_mbcnt_hi_u32_b32 v128, -1, v128
	s_lshl_b32 s18, s68, 9
	v_ashrrev_i32_e32 v129, 2, v128
	s_lshl_b32 s2, s96, 7
	v_and_b32_e32 v129, -4, v129
	s_ashr_i32 s19, s18, 31
	s_ashr_i32 s69, s68, 31
	s_or_b32 s2, s2, s58
	s_lshl_b64 s[0:1], s[68:69], 26
	v_add_u32_e32 v164, s2, v129
	s_lshl_b64 s[18:19], s[18:19], 2
	s_add_u32 s20, s73, s18
	v_ashrrev_i32_e32 v165, 31, v164
	s_addc_u32 s21, s46, s19
	v_lshlrev_b64 v[170:171], 2, v[164:165]
	v_lshl_add_u64 v[168:169], s[20:21], 0, v[170:171]
	global_load_dwordx4 v[132:135], v[168:169], off
	s_add_u32 s20, s71, s18
	s_addc_u32 s21, s48, s19
	s_add_u32 s18, s49, s18
	s_addc_u32 s19, s4, s19
	v_and_or_b32 v128, v128, 15, s57
	v_lshl_add_u64 v[166:167], s[18:19], 0, v[170:171]
	v_lshl_add_u32 v174, s44, 8, v128
	v_lshl_add_u64 v[172:173], s[20:21], 0, v[170:171]
	global_load_dwordx4 v[128:131], v[166:167], off
	global_load_dwordx4 v[136:139], v[172:173], off
	v_ashrrev_i32_e32 v175, 31, v174
	v_lshlrev_b64 v[176:177], 10, v[174:175]
	v_lshl_add_u64 v[180:181], s[14:15], 0, v[176:177]
	v_lshlrev_b64 v[176:177], 1, v[164:165]
	v_lshl_add_u64 v[164:165], v[180:181], 0, v[176:177]
	global_load_dwordx2 v[180:181], v[164:165], off
	s_add_u32 s44, s34, s0
	s_addc_u32 s45, s35, s1
	s_and_b64 vcc, exec, s[6:7]
	s_mov_b32 s96, s64
	s_mov_b32 s68, s76
	s_mov_b64 s[0:1], s[10:11]
	s_mov_b64 s[88:89], s[8:9]
	s_waitcnt vmcnt(0)
	v_add_f32_e32 v120, v120, v132
	v_mul_f32_e32 v120, 0xbfb8aa3b, v120
	v_exp_f32_e32 v120, v120
	v_add_f32_e32 v121, v121, v133
	v_add_f32_e32 v122, v122, v134
	v_mul_f32_e32 v121, 0xbfb8aa3b, v121
	v_mul_f32_e32 v122, 0xbfb8aa3b, v122
	v_exp_f32_e32 v121, v121
	v_exp_f32_e32 v122, v122
	v_add_f32_e32 v123, v123, v135
	v_mul_f32_e32 v123, 0xbfb8aa3b, v123
	v_exp_f32_e32 v123, v123
	v_add_f32_e32 v120, 1.0, v120
	v_rcp_f32_e32 v120, v120
	v_add_f32_e32 v121, 1.0, v121
	v_add_f32_e32 v122, 1.0, v122
	v_rcp_f32_e32 v121, v121
	v_rcp_f32_e32 v122, v122
	v_add_f32_e32 v123, 1.0, v123
	v_rcp_f32_e32 v123, v123
	s_waitcnt lgkmcnt(0)
	v_mul_f32_e32 v120, v128, v120
	v_add_f32_e32 v124, v124, v136
	v_add_f32_e32 v184, v120, v120
	v_mul_f32_e32 v124, 0xbfb8aa3b, v124
	v_exp_f32_e32 v184, v184
	v_mul_f32_e32 v121, v129, v121
	v_mul_f32_e32 v186, v130, v122
	v_exp_f32_e32 v124, v124
	v_add_f32_e32 v125, v125, v137
	v_add_f32_e32 v185, v121, v121
	v_add_f32_e32 v122, v186, v186
	v_mul_f32_e32 v125, 0xbfb8aa3b, v125
	v_exp_f32_e32 v185, v185
	v_exp_f32_e32 v122, v122
	v_mul_f32_e32 v187, v131, v123
	v_exp_f32_e32 v125, v125
	v_add_f32_e32 v126, v126, v138
	v_add_f32_e32 v123, v187, v187
	v_mul_f32_e32 v126, 0xbfb8aa3b, v126
	v_exp_f32_e32 v123, v123
	v_sub_f32_e32 v184, 1.0, v184
	v_exp_f32_e32 v126, v126
	v_add_f32_e32 v127, v127, v139
	v_add_f32_e32 v124, 1.0, v124
	v_max_f32_e32 v184, 0, v184
	v_mul_f32_e32 v127, 0xbfb8aa3b, v127
	v_rcp_f32_e32 v124, v124
	v_sqrt_f32_e32 v184, v184
	v_sub_f32_e32 v185, 1.0, v185
	v_sub_f32_e32 v122, 1.0, v122
	v_exp_f32_e32 v127, v127
	v_add_f32_e32 v125, 1.0, v125
	v_max_f32_e32 v185, 0, v185
	v_max_f32_e32 v122, 0, v122
	v_rcp_f32_e32 v125, v125
	v_sqrt_f32_e32 v185, v185
	v_sqrt_f32_e32 v188, v122
	v_sub_f32_e32 v122, 1.0, v123
	v_add_f32_e32 v126, 1.0, v126
	v_max_f32_e32 v122, 0, v122
	v_lshlrev_b32_e32 v182, 16, v180
	v_rcp_f32_e32 v126, v126
	v_sqrt_f32_e32 v189, v122
	v_mul_f32_e32 v122, v124, v184
	v_add_f32_e32 v127, 1.0, v127
	v_mul_f32_e32 v122, v122, v182
	v_and_b32_e32 v180, 0xffff0000, v180
	v_rcp_f32_e32 v127, v127
	v_cvt_pk_bf16_f32 v122, v120, v122
	v_mul_f32_e32 v120, v125, v185
	v_mul_f32_e32 v120, v120, v180
	v_lshlrev_b32_e32 v183, 16, v181
	v_cvt_pk_bf16_f32 v123, v121, v120
	v_mul_f32_e32 v120, v126, v188
	v_mul_f32_e32 v120, v120, v183
	v_and_b32_e32 v181, 0xffff0000, v181
	v_cvt_pk_bf16_f32 v124, v186, v120
	v_mul_f32_e32 v120, v127, v189
	v_mul_f32_e32 v120, v120, v181
	v_cvt_pk_bf16_f32 v125, v187, v120
	v_lshlrev_b64 v[120:121], 11, v[174:175]
	v_lshl_add_u64 v[120:121], s[44:45], 0, v[120:121]
	v_lshl_add_u64 v[120:121], v[120:121], 0, v[170:171]
	v_or_b32_e32 v190, 16, v174
	v_ashrrev_i32_e32 v191, 31, v190
	v_lshlrev_b64 v[192:193], 10, v[190:191]
	v_lshl_add_u64 v[194:195], s[14:15], 0, v[192:193]
	v_lshl_add_u64 v[196:197], v[194:195], 0, v[176:177]
	global_load_dwordx2 v[240:241], v[196:197], off
	global_store_dwordx4 v[120:121], v[122:125], off
	v_add_f32_e32 v116, v116, v132
	v_mul_f32_e32 v116, 0xbfb8aa3b, v116
	v_or_b32_e32 v124, 16, v174
	v_ashrrev_i32_e32 v125, 31, v124
	v_lshlrev_b64 v[122:123], 10, v[124:125]
	v_lshl_add_u64 v[122:123], s[14:15], 0, v[122:123]
	v_lshl_add_u64 v[122:123], v[122:123], 0, v[176:177]
	v_exp_f32_e32 v116, v116
	v_add_f32_e32 v117, v117, v133
	v_mul_f32_e32 v117, 0xbfb8aa3b, v117
	v_exp_f32_e32 v117, v117
	v_add_f32_e32 v118, v118, v134
	v_add_f32_e32 v114, v114, v138
	v_add_f32_e32 v115, v115, v139
	v_mul_f32_e32 v118, 0xbfb8aa3b, v118
	v_mul_f32_e32 v114, 0xbfb8aa3b, v114
	v_add_f32_e32 v119, v119, v135
	v_mul_f32_e32 v115, 0xbfb8aa3b, v115
	v_exp_f32_e32 v118, v118
	v_exp_f32_e32 v114, v114
	v_mul_f32_e32 v119, 0xbfb8aa3b, v119
	v_exp_f32_e32 v115, v115
	v_add_f32_e32 v116, 1.0, v116
	v_exp_f32_e32 v119, v119
	v_rcp_f32_e32 v116, v116
	v_add_f32_e32 v117, 1.0, v117
	v_rcp_f32_e32 v117, v117
	v_add_f32_e32 v118, 1.0, v118
	v_add_f32_e32 v114, 1.0, v114
	v_add_f32_e32 v115, 1.0, v115
	v_rcp_f32_e32 v118, v118
	v_rcp_f32_e32 v181, v114
	v_add_f32_e32 v114, 1.0, v119
	v_rcp_f32_e32 v119, v115
	v_mul_f32_e32 v115, v128, v116
	v_add_f32_e32 v112, v112, v136
	v_add_f32_e32 v116, v115, v115
	v_mul_f32_e32 v112, 0xbfb8aa3b, v112
	v_rcp_f32_e32 v114, v114
	v_exp_f32_e32 v116, v116
	v_mul_f32_e32 v117, v129, v117
	v_exp_f32_e32 v112, v112
	v_add_f32_e32 v113, v113, v137
	v_add_f32_e32 v182, v117, v117
	v_mul_f32_e32 v113, 0xbfb8aa3b, v113
	v_exp_f32_e32 v182, v182
	v_mul_f32_e32 v118, v130, v118
	v_exp_f32_e32 v113, v113
	v_add_f32_e32 v183, v118, v118
	v_exp_f32_e32 v183, v183
	v_mul_f32_e32 v184, v131, v114
	v_sub_f32_e32 v116, 1.0, v116
	v_add_f32_e32 v112, 1.0, v112
	v_add_f32_e32 v114, v184, v184
	v_max_f32_e32 v116, 0, v116
	v_rcp_f32_e32 v112, v112
	v_exp_f32_e32 v114, v114
	v_sqrt_f32_e32 v116, v116
	v_sub_f32_e32 v182, 1.0, v182
	v_add_f32_e32 v113, 1.0, v113
	v_max_f32_e32 v182, 0, v182
	v_rcp_f32_e32 v113, v113
	v_sqrt_f32_e32 v182, v182
	v_sub_f32_e32 v183, 1.0, v183
	v_max_f32_e32 v183, 0, v183
	v_sqrt_f32_e32 v183, v183
	v_sub_f32_e32 v114, 1.0, v114
	v_mul_f32_e32 v112, v112, v116
	v_max_f32_e32 v114, 0, v114
	v_sqrt_f32_e32 v185, v114
	v_add_f32_e32 v108, v108, v132
	v_mul_f32_e32 v108, 0xbfb8aa3b, v108
	v_exp_f32_e32 v108, v108
	v_add_f32_e32 v109, v109, v133
	v_mul_f32_e32 v109, 0xbfb8aa3b, v109
	v_exp_f32_e32 v109, v109
	v_add_f32_e32 v110, v110, v134
	v_add_f32_e32 v106, v106, v138
	v_add_f32_e32 v107, v107, v139
	v_mul_f32_e32 v110, 0xbfb8aa3b, v110
	v_mul_f32_e32 v106, 0xbfb8aa3b, v106
	v_add_f32_e32 v111, v111, v135
	v_mul_f32_e32 v107, 0xbfb8aa3b, v107
	v_exp_f32_e32 v110, v110
	v_exp_f32_e32 v106, v106
	v_mul_f32_e32 v111, 0xbfb8aa3b, v111
	s_waitcnt vmcnt(1)
	v_mov_b64_e32 v[126:127], v[240:241]
	v_lshlrev_b32_e32 v175, 16, v126
	v_mul_f32_e32 v112, v112, v175
	v_and_b32_e32 v126, 0xffff0000, v126
	v_cvt_pk_bf16_f32 v114, v115, v112
	v_mul_f32_e32 v112, v113, v182
	v_mul_f32_e32 v112, v112, v126
	v_lshlrev_b32_e32 v180, 16, v127
	v_cvt_pk_bf16_f32 v115, v117, v112
	v_mul_f32_e32 v112, v181, v183
	v_mul_f32_e32 v112, v112, v180
	v_and_b32_e32 v127, 0xffff0000, v127
	v_cvt_pk_bf16_f32 v116, v118, v112
	v_mul_f32_e32 v112, v119, v185
	v_mul_f32_e32 v112, v112, v127
	v_cvt_pk_bf16_f32 v117, v184, v112
	v_lshlrev_b64 v[112:113], 11, v[124:125]
	v_lshl_add_u64 v[112:113], s[44:45], 0, v[112:113]
	v_lshl_add_u64 v[112:113], v[112:113], 0, v[170:171]
	v_or_b32_e32 v190, 32, v174
	v_ashrrev_i32_e32 v191, 31, v190
	v_lshlrev_b64 v[192:193], 10, v[190:191]
	v_lshl_add_u64 v[194:195], s[14:15], 0, v[192:193]
	v_lshl_add_u64 v[196:197], v[194:195], 0, v[176:177]
	global_load_dwordx2 v[242:243], v[196:197], off
	global_store_dwordx4 v[112:113], v[114:117], off
	v_exp_f32_e32 v107, v107
	v_add_f32_e32 v108, 1.0, v108
	v_or_b32_e32 v116, 32, v174
	v_ashrrev_i32_e32 v117, 31, v116
	v_lshlrev_b64 v[114:115], 10, v[116:117]
	v_lshl_add_u64 v[114:115], s[14:15], 0, v[114:115]
	v_lshl_add_u64 v[114:115], v[114:115], 0, v[176:177]
	v_exp_f32_e32 v111, v111
	v_rcp_f32_e32 v108, v108
	v_add_f32_e32 v109, 1.0, v109
	v_rcp_f32_e32 v109, v109
	v_add_f32_e32 v110, 1.0, v110
	v_add_f32_e32 v106, 1.0, v106
	v_add_f32_e32 v107, 1.0, v107
	v_rcp_f32_e32 v110, v110
	v_rcp_f32_e32 v126, v106
	v_add_f32_e32 v106, 1.0, v111
	v_rcp_f32_e32 v111, v107
	v_mul_f32_e32 v107, v128, v108
	v_add_f32_e32 v104, v104, v136
	v_add_f32_e32 v108, v107, v107
	v_mul_f32_e32 v104, 0xbfb8aa3b, v104
	v_rcp_f32_e32 v106, v106
	v_exp_f32_e32 v108, v108
	v_mul_f32_e32 v109, v129, v109
	v_exp_f32_e32 v104, v104
	v_add_f32_e32 v105, v105, v137
	v_add_f32_e32 v127, v109, v109
	v_mul_f32_e32 v105, 0xbfb8aa3b, v105
	v_exp_f32_e32 v127, v127
	v_mul_f32_e32 v110, v130, v110
	v_exp_f32_e32 v105, v105
	v_add_f32_e32 v175, v110, v110
	v_exp_f32_e32 v175, v175
	v_mul_f32_e32 v180, v131, v106
	v_sub_f32_e32 v108, 1.0, v108
	v_add_f32_e32 v104, 1.0, v104
	v_add_f32_e32 v106, v180, v180
	v_max_f32_e32 v108, 0, v108
	v_rcp_f32_e32 v104, v104
	v_exp_f32_e32 v106, v106
	v_sqrt_f32_e32 v108, v108
	v_sub_f32_e32 v127, 1.0, v127
	v_add_f32_e32 v105, 1.0, v105
	v_max_f32_e32 v127, 0, v127
	v_rcp_f32_e32 v105, v105
	v_sqrt_f32_e32 v127, v127
	v_sub_f32_e32 v175, 1.0, v175
	v_max_f32_e32 v175, 0, v175
	v_sqrt_f32_e32 v175, v175
	v_sub_f32_e32 v106, 1.0, v106
	v_mul_f32_e32 v104, v104, v108
	v_max_f32_e32 v106, 0, v106
	v_sqrt_f32_e32 v181, v106
	v_add_f32_e32 v100, v100, v132
	v_mul_f32_e32 v100, 0xbfb8aa3b, v100
	v_exp_f32_e32 v100, v100
	v_add_f32_e32 v101, v101, v133
	v_mul_f32_e32 v101, 0xbfb8aa3b, v101
	v_exp_f32_e32 v101, v101
	v_add_f32_e32 v102, v102, v134
	v_add_f32_e32 v98, v98, v138
	v_add_f32_e32 v99, v99, v139
	v_mul_f32_e32 v102, 0xbfb8aa3b, v102
	v_mul_f32_e32 v98, 0xbfb8aa3b, v98
	v_add_f32_e32 v103, v103, v135
	v_mul_f32_e32 v99, 0xbfb8aa3b, v99
	v_exp_f32_e32 v102, v102
	v_exp_f32_e32 v98, v98
	v_mul_f32_e32 v103, 0xbfb8aa3b, v103
	v_exp_f32_e32 v99, v99
	v_add_f32_e32 v100, 1.0, v100
	v_exp_f32_e32 v103, v103
	v_rcp_f32_e32 v100, v100
	v_add_f32_e32 v101, 1.0, v101
	v_rcp_f32_e32 v101, v101
	v_add_f32_e32 v102, 1.0, v102
	v_add_f32_e32 v98, 1.0, v98
	v_add_f32_e32 v99, 1.0, v99
	v_rcp_f32_e32 v102, v102
	v_add_f32_e32 v96, v96, v136
	v_mul_f32_e32 v96, 0xbfb8aa3b, v96
	v_mul_f32_e32 v101, v129, v101
	v_exp_f32_e32 v96, v96
	v_add_f32_e32 v97, v97, v137
	v_mul_f32_e32 v97, 0xbfb8aa3b, v97
	s_waitcnt vmcnt(1)
	v_mov_b64_e32 v[118:119], v[242:243]
	v_lshlrev_b32_e32 v124, 16, v118
	v_mul_f32_e32 v104, v104, v124
	v_and_b32_e32 v118, 0xffff0000, v118
	v_cvt_pk_bf16_f32 v106, v107, v104
	v_mul_f32_e32 v104, v105, v127
	v_mul_f32_e32 v104, v104, v118
	v_lshlrev_b32_e32 v125, 16, v119
	v_cvt_pk_bf16_f32 v107, v109, v104
	v_mul_f32_e32 v104, v126, v175
	v_mul_f32_e32 v104, v104, v125
	v_and_b32_e32 v119, 0xffff0000, v119
	v_cvt_pk_bf16_f32 v108, v110, v104
	v_mul_f32_e32 v104, v111, v181
	v_mul_f32_e32 v104, v104, v119
	v_cvt_pk_bf16_f32 v109, v180, v104
	v_lshlrev_b64 v[104:105], 11, v[116:117]
	v_lshl_add_u64 v[104:105], s[44:45], 0, v[104:105]
	v_lshl_add_u64 v[104:105], v[104:105], 0, v[170:171]
	v_or_b32_e32 v190, 48, v174
	v_ashrrev_i32_e32 v191, 31, v190
	v_lshlrev_b64 v[192:193], 10, v[190:191]
	v_lshl_add_u64 v[194:195], s[14:15], 0, v[192:193]
	v_lshl_add_u64 v[196:197], v[194:195], 0, v[176:177]
	global_load_dwordx2 v[240:241], v[196:197], off
	global_store_dwordx4 v[104:105], v[106:109], off
	v_rcp_f32_e32 v118, v98
	v_add_f32_e32 v98, 1.0, v103
	v_or_b32_e32 v108, 48, v174
	v_ashrrev_i32_e32 v109, 31, v108
	v_lshlrev_b64 v[106:107], 10, v[108:109]
	v_lshl_add_u64 v[106:107], s[14:15], 0, v[106:107]
	v_lshl_add_u64 v[106:107], v[106:107], 0, v[176:177]
	v_rcp_f32_e32 v103, v99
	v_mul_f32_e32 v99, v128, v100
	v_add_f32_e32 v100, v99, v99
	v_rcp_f32_e32 v98, v98
	v_exp_f32_e32 v100, v100
	v_add_f32_e32 v119, v101, v101
	v_exp_f32_e32 v119, v119
	v_mul_f32_e32 v102, v130, v102
	v_exp_f32_e32 v97, v97
	v_add_f32_e32 v124, v102, v102
	v_exp_f32_e32 v124, v124
	v_mul_f32_e32 v125, v131, v98
	v_sub_f32_e32 v100, 1.0, v100
	v_add_f32_e32 v96, 1.0, v96
	v_add_f32_e32 v98, v125, v125
	v_max_f32_e32 v100, 0, v100
	v_rcp_f32_e32 v96, v96
	v_exp_f32_e32 v98, v98
	v_sqrt_f32_e32 v100, v100
	v_sub_f32_e32 v119, 1.0, v119
	v_add_f32_e32 v97, 1.0, v97
	v_max_f32_e32 v119, 0, v119
	v_rcp_f32_e32 v97, v97
	v_sqrt_f32_e32 v119, v119
	v_sub_f32_e32 v124, 1.0, v124
	v_max_f32_e32 v124, 0, v124
	v_sqrt_f32_e32 v124, v124
	v_sub_f32_e32 v98, 1.0, v98
	v_mul_f32_e32 v96, v96, v100
	v_max_f32_e32 v98, 0, v98
	v_sqrt_f32_e32 v126, v98
	v_add_f32_e32 v92, v92, v132
	v_mul_f32_e32 v92, 0xbfb8aa3b, v92
	v_exp_f32_e32 v92, v92
	v_add_f32_e32 v93, v93, v133
	v_mul_f32_e32 v93, 0xbfb8aa3b, v93
	v_exp_f32_e32 v93, v93
	v_add_f32_e32 v94, v94, v134
	v_add_f32_e32 v90, v90, v138
	v_add_f32_e32 v91, v91, v139
	v_mul_f32_e32 v94, 0xbfb8aa3b, v94
	v_mul_f32_e32 v90, 0xbfb8aa3b, v90
	v_add_f32_e32 v95, v95, v135
	v_mul_f32_e32 v91, 0xbfb8aa3b, v91
	v_exp_f32_e32 v94, v94
	v_exp_f32_e32 v90, v90
	v_mul_f32_e32 v95, 0xbfb8aa3b, v95
	v_exp_f32_e32 v91, v91
	v_add_f32_e32 v92, 1.0, v92
	v_exp_f32_e32 v95, v95
	v_rcp_f32_e32 v92, v92
	v_add_f32_e32 v93, 1.0, v93
	v_rcp_f32_e32 v93, v93
	v_add_f32_e32 v94, 1.0, v94
	v_add_f32_e32 v90, 1.0, v90
	v_add_f32_e32 v91, 1.0, v91
	v_rcp_f32_e32 v94, v94
	v_add_f32_e32 v88, v88, v136
	v_mul_f32_e32 v88, 0xbfb8aa3b, v88
	v_mul_f32_e32 v93, v129, v93
	v_exp_f32_e32 v88, v88
	v_add_f32_e32 v89, v89, v137
	v_mul_f32_e32 v89, 0xbfb8aa3b, v89
	v_mul_f32_e32 v94, v130, v94
	v_exp_f32_e32 v89, v89
	v_add_f32_e32 v88, 1.0, v88
	v_rcp_f32_e32 v88, v88
	v_add_f32_e32 v84, v84, v132
	v_add_f32_e32 v89, 1.0, v89
	v_rcp_f32_e32 v89, v89
	v_mul_f32_e32 v84, 0xbfb8aa3b, v84
	v_exp_f32_e32 v84, v84
	v_add_f32_e32 v85, v85, v133
	v_mul_f32_e32 v85, 0xbfb8aa3b, v85
	v_exp_f32_e32 v85, v85
	v_add_f32_e32 v86, v86, v134
	v_mul_f32_e32 v86, 0xbfb8aa3b, v86
	v_exp_f32_e32 v86, v86
	v_add_f32_e32 v87, v87, v135
	s_waitcnt vmcnt(1)
	v_mov_b64_e32 v[110:111], v[240:241]
	v_lshlrev_b32_e32 v116, 16, v110
	v_mul_f32_e32 v96, v96, v116
	v_and_b32_e32 v110, 0xffff0000, v110
	v_cvt_pk_bf16_f32 v98, v99, v96
	v_mul_f32_e32 v96, v97, v119
	v_mul_f32_e32 v96, v96, v110
	v_lshlrev_b32_e32 v117, 16, v111
	v_cvt_pk_bf16_f32 v99, v101, v96
	v_mul_f32_e32 v96, v118, v124
	v_mul_f32_e32 v96, v96, v117
	v_and_b32_e32 v111, 0xffff0000, v111
	v_cvt_pk_bf16_f32 v100, v102, v96
	v_mul_f32_e32 v96, v103, v126
	v_mul_f32_e32 v96, v96, v111
	v_cvt_pk_bf16_f32 v101, v125, v96
	v_lshlrev_b64 v[96:97], 11, v[108:109]
	v_lshl_add_u64 v[96:97], s[44:45], 0, v[96:97]
	v_lshl_add_u64 v[96:97], v[96:97], 0, v[170:171]
	v_add_u32_e32 v190, 0x80, v174
	v_ashrrev_i32_e32 v191, 31, v190
	v_lshlrev_b64 v[192:193], 10, v[190:191]
	v_lshl_add_u64 v[194:195], s[14:15], 0, v[192:193]
	v_lshl_add_u64 v[196:197], v[194:195], 0, v[176:177]
	global_load_dwordx2 v[242:243], v[196:197], off
	global_store_dwordx4 v[96:97], v[98:101], off
	v_rcp_f32_e32 v110, v90
	v_add_f32_e32 v90, 1.0, v95
	v_add_u32_e32 v100, 0x80, v174
	v_ashrrev_i32_e32 v101, 31, v100
	v_lshlrev_b64 v[98:99], 10, v[100:101]
	v_lshl_add_u64 v[98:99], s[14:15], 0, v[98:99]
	v_lshl_add_u64 v[98:99], v[98:99], 0, v[176:177]
	v_rcp_f32_e32 v95, v91
	v_mul_f32_e32 v91, v128, v92
	v_add_f32_e32 v92, v91, v91
	v_rcp_f32_e32 v90, v90
	v_exp_f32_e32 v92, v92
	v_add_f32_e32 v111, v93, v93
	v_exp_f32_e32 v111, v111
	v_add_f32_e32 v116, v94, v94
	v_exp_f32_e32 v116, v116
	v_mul_f32_e32 v117, v131, v90
	v_sub_f32_e32 v92, 1.0, v92
	v_add_f32_e32 v90, v117, v117
	v_max_f32_e32 v92, 0, v92
	v_exp_f32_e32 v90, v90
	v_sqrt_f32_e32 v92, v92
	v_sub_f32_e32 v111, 1.0, v111
	v_max_f32_e32 v111, 0, v111
	v_sqrt_f32_e32 v111, v111
	v_sub_f32_e32 v116, 1.0, v116
	v_max_f32_e32 v116, 0, v116
	v_sqrt_f32_e32 v116, v116
	v_sub_f32_e32 v90, 1.0, v90
	v_mul_f32_e32 v88, v88, v92
	v_max_f32_e32 v90, 0, v90
	v_sqrt_f32_e32 v118, v90
	v_add_f32_e32 v84, 1.0, v84
	v_mul_f32_e32 v87, 0xbfb8aa3b, v87
	v_rcp_f32_e32 v84, v84
	v_exp_f32_e32 v87, v87
	v_add_f32_e32 v85, 1.0, v85
	v_rcp_f32_e32 v85, v85
	v_add_f32_e32 v86, 1.0, v86
	v_rcp_f32_e32 v86, v86
	v_mul_f32_e32 v84, v128, v84
	v_add_f32_e32 v80, v80, v136
	v_add_f32_e32 v87, 1.0, v87
	v_mul_f32_e32 v80, 0xbfb8aa3b, v80
	v_rcp_f32_e32 v87, v87
	v_mul_f32_e32 v85, v129, v85
	v_exp_f32_e32 v80, v80
	v_add_f32_e32 v81, v81, v137
	v_mul_f32_e32 v81, 0xbfb8aa3b, v81
	v_mul_f32_e32 v86, v130, v86
	v_exp_f32_e32 v81, v81
	v_add_f32_e32 v82, v82, v138
	v_mul_f32_e32 v82, 0xbfb8aa3b, v82
	v_mul_f32_e32 v87, v131, v87
	v_exp_f32_e32 v82, v82
	v_add_f32_e32 v83, v83, v139
	v_add_f32_e32 v80, 1.0, v80
	v_mul_f32_e32 v83, 0xbfb8aa3b, v83
	v_rcp_f32_e32 v80, v80
	v_exp_f32_e32 v83, v83
	v_add_f32_e32 v81, 1.0, v81
	v_rcp_f32_e32 v81, v81
	v_add_f32_e32 v82, 1.0, v82
	v_rcp_f32_e32 v82, v82
	v_add_f32_e32 v83, 1.0, v83
	v_rcp_f32_e32 v83, v83
	v_add_f32_e32 v76, v76, v132
	v_add_f32_e32 v77, v77, v133
	v_mul_f32_e32 v76, 0xbfb8aa3b, v76
	v_mul_f32_e32 v77, 0xbfb8aa3b, v77
	v_exp_f32_e32 v76, v76
	v_exp_f32_e32 v77, v77
	v_add_f32_e32 v78, v78, v134
	v_add_f32_e32 v79, v79, v135
	v_mul_f32_e32 v78, 0xbfb8aa3b, v78
	v_mul_f32_e32 v79, 0xbfb8aa3b, v79
	v_exp_f32_e32 v78, v78
	v_exp_f32_e32 v79, v79
	v_add_f32_e32 v76, 1.0, v76
	v_add_f32_e32 v77, 1.0, v77
	v_rcp_f32_e32 v76, v76
	v_rcp_f32_e32 v77, v77
	v_add_f32_e32 v78, 1.0, v78
	v_add_f32_e32 v79, 1.0, v79
	v_rcp_f32_e32 v78, v78
	v_rcp_f32_e32 v79, v79
	s_waitcnt vmcnt(1)
	v_mov_b64_e32 v[102:103], v[242:243]
	v_lshlrev_b32_e32 v108, 16, v102
	v_mul_f32_e32 v88, v88, v108
	v_and_b32_e32 v102, 0xffff0000, v102
	v_cvt_pk_bf16_f32 v90, v91, v88
	v_mul_f32_e32 v88, v89, v111
	v_mul_f32_e32 v88, v88, v102
	v_lshlrev_b32_e32 v109, 16, v103
	v_cvt_pk_bf16_f32 v91, v93, v88
	v_mul_f32_e32 v88, v110, v116
	v_mul_f32_e32 v88, v88, v109
	v_and_b32_e32 v103, 0xffff0000, v103
	v_cvt_pk_bf16_f32 v92, v94, v88
	v_mul_f32_e32 v88, v95, v118
	v_mul_f32_e32 v88, v88, v103
	v_cvt_pk_bf16_f32 v93, v117, v88
	v_lshlrev_b64 v[88:89], 11, v[100:101]
	v_lshl_add_u64 v[88:89], s[44:45], 0, v[88:89]
	v_lshl_add_u64 v[88:89], v[88:89], 0, v[170:171]
	v_add_u32_e32 v190, 0x90, v174
	v_ashrrev_i32_e32 v191, 31, v190
	v_lshlrev_b64 v[192:193], 10, v[190:191]
	v_lshl_add_u64 v[194:195], s[14:15], 0, v[192:193]
	v_lshl_add_u64 v[196:197], v[194:195], 0, v[176:177]
	global_load_dwordx2 v[240:241], v[196:197], off
	global_store_dwordx4 v[88:89], v[90:93], off
	v_add_f32_e32 v102, v84, v84
	v_exp_f32_e32 v102, v102
	v_add_u32_e32 v92, 0x90, v174
	v_ashrrev_i32_e32 v93, 31, v92
	v_lshlrev_b64 v[90:91], 10, v[92:93]
	v_lshl_add_u64 v[90:91], s[14:15], 0, v[90:91]
	v_lshl_add_u64 v[90:91], v[90:91], 0, v[176:177]
	v_add_f32_e32 v103, v85, v85
	v_exp_f32_e32 v103, v103
	v_add_f32_e32 v108, v86, v86
	v_exp_f32_e32 v108, v108
	v_sub_f32_e32 v102, 1.0, v102
	v_add_f32_e32 v109, v87, v87
	v_max_f32_e32 v102, 0, v102
	v_exp_f32_e32 v109, v109
	v_sqrt_f32_e32 v102, v102
	v_sub_f32_e32 v103, 1.0, v103
	v_max_f32_e32 v103, 0, v103
	v_sqrt_f32_e32 v103, v103
	v_sub_f32_e32 v108, 1.0, v108
	v_max_f32_e32 v108, 0, v108
	v_sqrt_f32_e32 v108, v108
	v_sub_f32_e32 v109, 1.0, v109
	v_mul_f32_e32 v80, v80, v102
	v_max_f32_e32 v109, 0, v109
	v_sqrt_f32_e32 v109, v109
	v_mul_f32_e32 v76, v128, v76
	v_mul_f32_e32 v77, v129, v77
	v_add_f32_e32 v72, v72, v136
	v_add_f32_e32 v73, v73, v137
	v_mul_f32_e32 v72, 0xbfb8aa3b, v72
	v_mul_f32_e32 v73, 0xbfb8aa3b, v73
	v_mul_f32_e32 v78, v130, v78
	v_mul_f32_e32 v79, v131, v79
	v_exp_f32_e32 v72, v72
	v_exp_f32_e32 v73, v73
	v_add_f32_e32 v74, v74, v138
	v_add_f32_e32 v75, v75, v139
	v_mul_f32_e32 v74, 0xbfb8aa3b, v74
	v_mul_f32_e32 v75, 0xbfb8aa3b, v75
	v_exp_f32_e32 v74, v74
	v_exp_f32_e32 v75, v75
	v_add_f32_e32 v72, 1.0, v72
	v_add_f32_e32 v73, 1.0, v73
	v_rcp_f32_e32 v72, v72
	v_rcp_f32_e32 v73, v73
	v_add_f32_e32 v74, 1.0, v74
	v_add_f32_e32 v75, 1.0, v75
	v_rcp_f32_e32 v74, v74
	v_rcp_f32_e32 v75, v75
	v_add_f32_e32 v52, v52, v132
	v_add_f32_e32 v53, v53, v133
	v_mul_f32_e32 v52, 0xbfb8aa3b, v52
	v_mul_f32_e32 v53, 0xbfb8aa3b, v53
	v_exp_f32_e32 v52, v52
	v_exp_f32_e32 v53, v53
	v_add_f32_e32 v54, v54, v134
	v_add_f32_e32 v55, v55, v135
	v_mul_f32_e32 v54, 0xbfb8aa3b, v54
	v_mul_f32_e32 v55, 0xbfb8aa3b, v55
	v_exp_f32_e32 v54, v54
	v_exp_f32_e32 v55, v55
	v_add_f32_e32 v52, 1.0, v52
	v_add_f32_e32 v53, 1.0, v53
	v_rcp_f32_e32 v52, v52
	v_rcp_f32_e32 v53, v53
	v_add_f32_e32 v54, 1.0, v54
	v_add_f32_e32 v55, 1.0, v55
	v_rcp_f32_e32 v54, v54
	v_rcp_f32_e32 v55, v55
	v_mul_f32_e32 v52, v128, v52
	v_mul_f32_e32 v53, v129, v53
	v_add_f32_e32 v48, v48, v136
	v_add_f32_e32 v49, v49, v137
	v_mul_f32_e32 v48, 0xbfb8aa3b, v48
	v_mul_f32_e32 v49, 0xbfb8aa3b, v49
	v_exp_f32_e32 v48, v48
	v_exp_f32_e32 v49, v49
	v_mul_f32_e32 v54, v130, v54
	v_mul_f32_e32 v55, v131, v55
	v_add_f32_e32 v50, v50, v138
	v_add_f32_e32 v51, v51, v139
	v_mul_f32_e32 v50, 0xbfb8aa3b, v50
	v_mul_f32_e32 v51, 0xbfb8aa3b, v51
	v_exp_f32_e32 v50, v50
	v_exp_f32_e32 v51, v51
	s_waitcnt vmcnt(1)
	v_mov_b64_e32 v[94:95], v[240:241]
	v_lshlrev_b32_e32 v100, 16, v94
	v_mul_f32_e32 v80, v80, v100
	v_and_b32_e32 v94, 0xffff0000, v94
	v_cvt_pk_bf16_f32 v84, v84, v80
	v_mul_f32_e32 v80, v81, v103
	v_mul_f32_e32 v80, v80, v94
	v_lshlrev_b32_e32 v101, 16, v95
	v_cvt_pk_bf16_f32 v85, v85, v80
	v_mul_f32_e32 v80, v82, v108
	v_mul_f32_e32 v80, v80, v101
	v_and_b32_e32 v95, 0xffff0000, v95
	v_cvt_pk_bf16_f32 v86, v86, v80
	v_mul_f32_e32 v80, v83, v109
	v_mul_f32_e32 v80, v80, v95
	v_cvt_pk_bf16_f32 v87, v87, v80
	v_lshlrev_b64 v[80:81], 11, v[92:93]
	v_lshl_add_u64 v[80:81], s[44:45], 0, v[80:81]
	v_lshl_add_u64 v[82:83], v[80:81], 0, v[170:171]
	v_add_u32_e32 v80, 0xa0, v174
	v_ashrrev_i32_e32 v81, 31, v80
	v_lshlrev_b64 v[190:191], 10, v[80:81]
	v_lshl_add_u64 v[192:193], s[14:15], 0, v[190:191]
	v_lshl_add_u64 v[194:195], v[192:193], 0, v[176:177]
	global_load_dwordx2 v[242:243], v[194:195], off
	global_store_dwordx4 v[82:83], v[84:87], off
	v_add_f32_e32 v94, v76, v76
	v_add_f32_e32 v95, v77, v77
	v_lshlrev_b64 v[84:85], 10, v[80:81]
	v_lshl_add_u64 v[84:85], s[14:15], 0, v[84:85]
	v_lshl_add_u64 v[84:85], v[84:85], 0, v[176:177]
	v_exp_f32_e32 v94, v94
	v_exp_f32_e32 v95, v95
	v_add_f32_e32 v100, v78, v78
	v_add_f32_e32 v101, v79, v79
	v_exp_f32_e32 v100, v100
	v_exp_f32_e32 v101, v101
	v_sub_f32_e32 v94, 1.0, v94
	v_sub_f32_e32 v95, 1.0, v95
	v_max_f32_e32 v94, 0, v94
	v_max_f32_e32 v95, 0, v95
	v_sqrt_f32_e32 v94, v94
	v_sqrt_f32_e32 v95, v95
	v_sub_f32_e32 v100, 1.0, v100
	v_sub_f32_e32 v101, 1.0, v101
	v_max_f32_e32 v100, 0, v100
	v_max_f32_e32 v101, 0, v101
	v_sqrt_f32_e32 v100, v100
	v_sqrt_f32_e32 v101, v101
	v_mul_f32_e32 v72, v72, v94
	v_mul_f32_e32 v73, v73, v95
	v_mul_f32_e32 v74, v74, v100
	v_mul_f32_e32 v75, v75, v101
	v_add_f32_e32 v48, 1.0, v48
	v_add_f32_e32 v49, 1.0, v49
	v_rcp_f32_e32 v48, v48
	v_rcp_f32_e32 v49, v49
	v_add_f32_e32 v50, 1.0, v50
	v_add_f32_e32 v51, 1.0, v51
	v_rcp_f32_e32 v50, v50
	v_rcp_f32_e32 v51, v51
	s_waitcnt vmcnt(1)
	v_mov_b64_e32 v[86:87], v[242:243]
	v_lshlrev_b32_e32 v92, 16, v86
	v_and_b32_e32 v86, 0xffff0000, v86
	v_mul_f32_e32 v72, v72, v92
	v_mul_f32_e32 v73, v73, v86
	v_lshlrev_b32_e32 v93, 16, v87
	v_and_b32_e32 v87, 0xffff0000, v87
	v_cvt_pk_bf16_f32 v72, v76, v72
	v_cvt_pk_bf16_f32 v73, v77, v73
	v_lshlrev_b64 v[76:77], 11, v[80:81]
	v_mul_f32_e32 v74, v74, v93
	v_mul_f32_e32 v75, v75, v87
	v_lshl_add_u64 v[76:77], s[44:45], 0, v[76:77]
	v_cvt_pk_bf16_f32 v74, v78, v74
	v_cvt_pk_bf16_f32 v75, v79, v75
	v_lshl_add_u64 v[78:79], v[76:77], 0, v[170:171]
	v_add_u32_e32 v190, 0xb0, v174
	v_ashrrev_i32_e32 v191, 31, v190
	v_lshlrev_b64 v[192:193], 10, v[190:191]
	v_lshl_add_u64 v[194:195], s[14:15], 0, v[192:193]
	v_lshl_add_u64 v[196:197], v[194:195], 0, v[176:177]
	global_load_dwordx2 v[240:241], v[196:197], off
	global_store_dwordx4 v[78:79], v[72:75], off
	v_add_f32_e32 v86, v52, v52
	v_add_f32_e32 v87, v53, v53
	v_add_u32_e32 v72, 0xb0, v174
	v_ashrrev_i32_e32 v73, 31, v72
	v_lshlrev_b64 v[74:75], 10, v[72:73]
	v_lshl_add_u64 v[74:75], s[14:15], 0, v[74:75]
	v_lshl_add_u64 v[80:81], v[74:75], 0, v[176:177]
	v_exp_f32_e32 v86, v86
	v_exp_f32_e32 v87, v87
	v_add_f32_e32 v92, v54, v54
	v_add_f32_e32 v93, v55, v55
	v_exp_f32_e32 v92, v92
	v_exp_f32_e32 v93, v93
	v_sub_f32_e32 v86, 1.0, v86
	v_sub_f32_e32 v87, 1.0, v87
	v_max_f32_e32 v86, 0, v86
	v_max_f32_e32 v87, 0, v87
	v_sqrt_f32_e32 v86, v86
	v_sqrt_f32_e32 v87, v87
	v_sub_f32_e32 v92, 1.0, v92
	v_sub_f32_e32 v93, 1.0, v93
	v_max_f32_e32 v92, 0, v92
	v_max_f32_e32 v93, 0, v93
	v_sqrt_f32_e32 v92, v92
	v_sqrt_f32_e32 v93, v93
	v_mul_f32_e32 v48, v48, v86
	v_mul_f32_e32 v49, v49, v87
	v_mul_f32_e32 v50, v50, v92
	v_mul_f32_e32 v51, v51, v93
	s_waitcnt vmcnt(1)
	v_mov_b64_e32 v[74:75], v[240:241]
	v_lshlrev_b32_e32 v76, 16, v74
	v_and_b32_e32 v74, 0xffff0000, v74
	v_mul_f32_e32 v48, v48, v76
	v_mul_f32_e32 v49, v49, v74
	v_cvt_pk_bf16_f32 v48, v52, v48
	v_cvt_pk_bf16_f32 v49, v53, v49
	v_lshlrev_b64 v[52:53], 11, v[72:73]
	v_lshlrev_b32_e32 v77, 16, v75
	v_and_b32_e32 v75, 0xffff0000, v75
	v_lshl_add_u64 v[52:53], s[44:45], 0, v[52:53]
	v_mul_f32_e32 v50, v50, v77
	v_mul_f32_e32 v51, v51, v75
	v_lshl_add_u64 v[76:77], v[52:53], 0, v[170:171]
	v_cvt_pk_bf16_f32 v50, v54, v50
	v_cvt_pk_bf16_f32 v51, v55, v51
	global_store_dwordx4 v[76:77], v[48:51], off
	global_load_dwordx4 v[52:55], v[168:169], off offset:64
	s_nop 0
	global_load_dwordx4 v[48:51], v[172:173], off offset:64
	global_load_dwordx4 v[72:75], v[166:167], off offset:64
	global_load_dwordx2 v[86:87], v[164:165], off offset:32
	s_mov_b32 s44, s16
	s_waitcnt vmcnt(0)
	v_add_f32_e32 v68, v68, v52
	v_add_f32_e32 v69, v69, v53
	v_add_f32_e32 v70, v70, v54
	v_add_f32_e32 v71, v71, v55
	v_mul_f32_e32 v68, 0xbfb8aa3b, v68
	v_mul_f32_e32 v69, 0xbfb8aa3b, v69
	v_mul_f32_e32 v70, 0xbfb8aa3b, v70
	v_mul_f32_e32 v71, 0xbfb8aa3b, v71
	v_exp_f32_e32 v68, v68
	v_exp_f32_e32 v69, v69
	v_exp_f32_e32 v70, v70
	v_exp_f32_e32 v71, v71
	v_add_f32_e32 v68, 1.0, v68
	v_add_f32_e32 v69, 1.0, v69
	v_add_f32_e32 v70, 1.0, v70
	v_add_f32_e32 v71, 1.0, v71
	v_rcp_f32_e32 v68, v68
	v_rcp_f32_e32 v69, v69
	v_rcp_f32_e32 v70, v70
	v_rcp_f32_e32 v71, v71
	s_waitcnt lgkmcnt(0)
	v_mul_f32_e32 v68, v72, v68
	v_mul_f32_e32 v69, v73, v69
	v_mul_f32_e32 v70, v74, v70
	v_mul_f32_e32 v71, v75, v71
	v_add_f32_e32 v64, v64, v48
	v_add_f32_e32 v65, v65, v49
	v_add_f32_e32 v66, v66, v50
	v_add_f32_e32 v67, v67, v51
	v_add_f32_e32 v94, v68, v68
	v_add_f32_e32 v95, v69, v69
	v_add_f32_e32 v100, v70, v70
	v_add_f32_e32 v101, v71, v71
	v_mul_f32_e32 v64, 0xbfb8aa3b, v64
	v_mul_f32_e32 v65, 0xbfb8aa3b, v65
	v_mul_f32_e32 v66, 0xbfb8aa3b, v66
	v_mul_f32_e32 v67, 0xbfb8aa3b, v67
	v_exp_f32_e32 v94, v94
	v_exp_f32_e32 v95, v95
	v_exp_f32_e32 v100, v100
	v_exp_f32_e32 v101, v101
	v_exp_f32_e32 v64, v64
	v_exp_f32_e32 v65, v65
	v_exp_f32_e32 v66, v66
	v_exp_f32_e32 v67, v67
	v_sub_f32_e32 v94, 1.0, v94
	v_sub_f32_e32 v95, 1.0, v95
	v_sub_f32_e32 v100, 1.0, v100
	v_sub_f32_e32 v101, 1.0, v101
	v_add_f32_e32 v64, 1.0, v64
	v_add_f32_e32 v65, 1.0, v65
	v_add_f32_e32 v66, 1.0, v66
	v_add_f32_e32 v67, 1.0, v67
	v_max_f32_e32 v94, 0, v94
	v_max_f32_e32 v95, 0, v95
	v_max_f32_e32 v100, 0, v100
	v_max_f32_e32 v101, 0, v101
	v_rcp_f32_e32 v64, v64
	v_rcp_f32_e32 v65, v65
	v_rcp_f32_e32 v66, v66
	v_rcp_f32_e32 v67, v67
	v_sqrt_f32_e32 v94, v94
	v_sqrt_f32_e32 v95, v95
	v_sqrt_f32_e32 v100, v100
	v_sqrt_f32_e32 v101, v101
	v_lshlrev_b32_e32 v92, 16, v86
	v_and_b32_e32 v86, 0xffff0000, v86
	v_lshlrev_b32_e32 v93, 16, v87
	v_and_b32_e32 v87, 0xffff0000, v87
	v_mul_f32_e32 v64, v64, v94
	v_mul_f32_e32 v65, v65, v95
	v_mul_f32_e32 v66, v66, v100
	v_mul_f32_e32 v67, v67, v101
	v_mul_f32_e32 v64, v64, v92
	v_mul_f32_e32 v65, v65, v86
	v_mul_f32_e32 v66, v66, v93
	v_mul_f32_e32 v67, v67, v87
	v_cvt_pk_bf16_f32 v64, v68, v64
	v_cvt_pk_bf16_f32 v65, v69, v65
	v_cvt_pk_bf16_f32 v66, v70, v66
	v_cvt_pk_bf16_f32 v67, v71, v67
	global_load_dwordx2 v[242:243], v[122:123], off offset:32
	global_store_dwordx4 v[120:121], v[64:67], off offset:64
	v_add_f32_e32 v60, v60, v52
	v_add_f32_e32 v61, v61, v53
	v_add_f32_e32 v62, v62, v54
	v_add_f32_e32 v63, v63, v55
	v_mul_f32_e32 v60, 0xbfb8aa3b, v60
	v_mul_f32_e32 v61, 0xbfb8aa3b, v61
	v_mul_f32_e32 v62, 0xbfb8aa3b, v62
	v_mul_f32_e32 v63, 0xbfb8aa3b, v63
	v_exp_f32_e32 v60, v60
	v_exp_f32_e32 v61, v61
	v_exp_f32_e32 v62, v62
	v_exp_f32_e32 v63, v63
	v_add_f32_e32 v60, 1.0, v60
	v_add_f32_e32 v61, 1.0, v61
	v_add_f32_e32 v62, 1.0, v62
	v_add_f32_e32 v63, 1.0, v63
	v_rcp_f32_e32 v60, v60
	v_rcp_f32_e32 v61, v61
	v_rcp_f32_e32 v62, v62
	v_rcp_f32_e32 v63, v63
	v_mul_f32_e32 v60, v72, v60
	v_mul_f32_e32 v61, v73, v61
	v_mul_f32_e32 v62, v74, v62
	v_mul_f32_e32 v63, v75, v63
	v_add_f32_e32 v56, v56, v48
	v_add_f32_e32 v57, v57, v49
	v_add_f32_e32 v58, v58, v50
	v_add_f32_e32 v59, v59, v51
	v_add_f32_e32 v68, v60, v60
	v_add_f32_e32 v69, v61, v61
	v_add_f32_e32 v70, v62, v62
	v_add_f32_e32 v71, v63, v63
	v_mul_f32_e32 v56, 0xbfb8aa3b, v56
	v_mul_f32_e32 v57, 0xbfb8aa3b, v57
	v_mul_f32_e32 v58, 0xbfb8aa3b, v58
	v_mul_f32_e32 v59, 0xbfb8aa3b, v59
	v_exp_f32_e32 v68, v68
	v_exp_f32_e32 v69, v69
	v_exp_f32_e32 v70, v70
	v_exp_f32_e32 v71, v71
	v_exp_f32_e32 v56, v56
	v_exp_f32_e32 v57, v57
	v_exp_f32_e32 v58, v58
	v_exp_f32_e32 v59, v59
	v_sub_f32_e32 v68, 1.0, v68
	v_sub_f32_e32 v69, 1.0, v69
	v_sub_f32_e32 v70, 1.0, v70
	v_sub_f32_e32 v71, 1.0, v71
	v_add_f32_e32 v56, 1.0, v56
	v_add_f32_e32 v57, 1.0, v57
	v_add_f32_e32 v58, 1.0, v58
	v_add_f32_e32 v59, 1.0, v59
	v_max_f32_e32 v68, 0, v68
	v_max_f32_e32 v69, 0, v69
	v_max_f32_e32 v70, 0, v70
	v_max_f32_e32 v71, 0, v71
	v_rcp_f32_e32 v56, v56
	v_rcp_f32_e32 v57, v57
	v_rcp_f32_e32 v58, v58
	v_rcp_f32_e32 v59, v59
	v_sqrt_f32_e32 v68, v68
	v_sqrt_f32_e32 v69, v69
	v_sqrt_f32_e32 v70, v70
	v_sqrt_f32_e32 v71, v71
	v_mul_f32_e32 v56, v56, v68
	v_mul_f32_e32 v57, v57, v69
	v_mul_f32_e32 v58, v58, v70
	v_mul_f32_e32 v59, v59, v71
	v_add_f32_e32 v44, v44, v52
	v_add_f32_e32 v45, v45, v53
	v_add_f32_e32 v46, v46, v54
	v_add_f32_e32 v47, v47, v55
	v_mul_f32_e32 v44, 0xbfb8aa3b, v44
	v_mul_f32_e32 v45, 0xbfb8aa3b, v45
	v_mul_f32_e32 v46, 0xbfb8aa3b, v46
	v_mul_f32_e32 v47, 0xbfb8aa3b, v47
	v_exp_f32_e32 v44, v44
	v_exp_f32_e32 v45, v45
	v_exp_f32_e32 v46, v46
	s_waitcnt vmcnt(1)
	v_mov_b64_e32 v[64:65], v[242:243]
	v_lshlrev_b32_e32 v66, 16, v64
	v_and_b32_e32 v64, 0xffff0000, v64
	v_lshlrev_b32_e32 v67, 16, v65
	v_and_b32_e32 v65, 0xffff0000, v65
	v_mul_f32_e32 v56, v56, v66
	v_mul_f32_e32 v57, v57, v64
	v_mul_f32_e32 v58, v58, v67
	v_mul_f32_e32 v59, v59, v65
	v_cvt_pk_bf16_f32 v56, v60, v56
	v_cvt_pk_bf16_f32 v57, v61, v57
	v_cvt_pk_bf16_f32 v58, v62, v58
	v_cvt_pk_bf16_f32 v59, v63, v59
	global_load_dwordx2 v[240:241], v[114:115], off offset:32
	global_store_dwordx4 v[112:113], v[56:59], off offset:64
	v_exp_f32_e32 v47, v47
	v_add_f32_e32 v44, 1.0, v44
	v_add_f32_e32 v45, 1.0, v45
	v_add_f32_e32 v46, 1.0, v46
	v_add_f32_e32 v47, 1.0, v47
	v_rcp_f32_e32 v44, v44
	v_rcp_f32_e32 v45, v45
	v_rcp_f32_e32 v46, v46
	v_rcp_f32_e32 v47, v47
	v_mul_f32_e32 v44, v72, v44
	v_mul_f32_e32 v45, v73, v45
	v_mul_f32_e32 v46, v74, v46
	v_mul_f32_e32 v47, v75, v47
	v_add_f32_e32 v40, v40, v48
	v_add_f32_e32 v41, v41, v49
	v_add_f32_e32 v42, v42, v50
	v_add_f32_e32 v43, v43, v51
	v_add_f32_e32 v60, v44, v44
	v_add_f32_e32 v61, v45, v45
	v_add_f32_e32 v62, v46, v46
	v_add_f32_e32 v63, v47, v47
	v_mul_f32_e32 v40, 0xbfb8aa3b, v40
	v_mul_f32_e32 v41, 0xbfb8aa3b, v41
	v_mul_f32_e32 v42, 0xbfb8aa3b, v42
	v_mul_f32_e32 v43, 0xbfb8aa3b, v43
	v_exp_f32_e32 v60, v60
	v_exp_f32_e32 v61, v61
	v_exp_f32_e32 v62, v62
	v_exp_f32_e32 v63, v63
	v_exp_f32_e32 v40, v40
	v_exp_f32_e32 v41, v41
	v_exp_f32_e32 v42, v42
	v_exp_f32_e32 v43, v43
	v_sub_f32_e32 v60, 1.0, v60
	v_sub_f32_e32 v61, 1.0, v61
	v_sub_f32_e32 v62, 1.0, v62
	v_sub_f32_e32 v63, 1.0, v63
	v_add_f32_e32 v40, 1.0, v40
	v_add_f32_e32 v41, 1.0, v41
	v_add_f32_e32 v42, 1.0, v42
	v_add_f32_e32 v43, 1.0, v43
	v_max_f32_e32 v60, 0, v60
	v_max_f32_e32 v61, 0, v61
	v_max_f32_e32 v62, 0, v62
	v_max_f32_e32 v63, 0, v63
	v_rcp_f32_e32 v40, v40
	v_rcp_f32_e32 v41, v41
	v_rcp_f32_e32 v42, v42
	v_rcp_f32_e32 v43, v43
	v_sqrt_f32_e32 v60, v60
	v_sqrt_f32_e32 v61, v61
	v_sqrt_f32_e32 v62, v62
	v_sqrt_f32_e32 v63, v63
	v_mul_f32_e32 v40, v40, v60
	v_mul_f32_e32 v41, v41, v61
	v_mul_f32_e32 v42, v42, v62
	v_mul_f32_e32 v43, v43, v63
	v_add_f32_e32 v36, v36, v52
	v_add_f32_e32 v37, v37, v53
	v_add_f32_e32 v38, v38, v54
	v_add_f32_e32 v39, v39, v55
	v_mul_f32_e32 v36, 0xbfb8aa3b, v36
	v_mul_f32_e32 v37, 0xbfb8aa3b, v37
	v_mul_f32_e32 v38, 0xbfb8aa3b, v38
	v_mul_f32_e32 v39, 0xbfb8aa3b, v39
	v_exp_f32_e32 v36, v36
	v_exp_f32_e32 v37, v37
	v_exp_f32_e32 v38, v38
	v_exp_f32_e32 v39, v39
	v_add_f32_e32 v36, 1.0, v36
	v_add_f32_e32 v37, 1.0, v37
	v_add_f32_e32 v38, 1.0, v38
	v_add_f32_e32 v39, 1.0, v39
	v_rcp_f32_e32 v36, v36
	v_rcp_f32_e32 v37, v37
	v_rcp_f32_e32 v38, v38
	v_rcp_f32_e32 v39, v39
	v_mul_f32_e32 v36, v72, v36
	v_mul_f32_e32 v37, v73, v37
	s_waitcnt vmcnt(1)
	v_mov_b64_e32 v[56:57], v[240:241]
	v_lshlrev_b32_e32 v58, 16, v56
	v_and_b32_e32 v56, 0xffff0000, v56
	v_lshlrev_b32_e32 v59, 16, v57
	v_and_b32_e32 v57, 0xffff0000, v57
	v_mul_f32_e32 v40, v40, v58
	v_mul_f32_e32 v41, v41, v56
	v_mul_f32_e32 v42, v42, v59
	v_mul_f32_e32 v43, v43, v57
	v_cvt_pk_bf16_f32 v40, v44, v40
	v_cvt_pk_bf16_f32 v41, v45, v41
	v_cvt_pk_bf16_f32 v42, v46, v42
	v_cvt_pk_bf16_f32 v43, v47, v43
	global_load_dwordx2 v[242:243], v[106:107], off offset:32
	global_store_dwordx4 v[104:105], v[40:43], off offset:64
	v_mul_f32_e32 v38, v74, v38
	v_mul_f32_e32 v39, v75, v39
	v_add_f32_e32 v32, v32, v48
	v_add_f32_e32 v33, v33, v49
	v_add_f32_e32 v34, v34, v50
	v_add_f32_e32 v35, v35, v51
	v_add_f32_e32 v44, v36, v36
	v_add_f32_e32 v45, v37, v37
	v_add_f32_e32 v46, v38, v38
	v_add_f32_e32 v47, v39, v39
	v_mul_f32_e32 v32, 0xbfb8aa3b, v32
	v_mul_f32_e32 v33, 0xbfb8aa3b, v33
	v_mul_f32_e32 v34, 0xbfb8aa3b, v34
	v_mul_f32_e32 v35, 0xbfb8aa3b, v35
	v_exp_f32_e32 v44, v44
	v_exp_f32_e32 v45, v45
	v_exp_f32_e32 v46, v46
	v_exp_f32_e32 v47, v47
	v_exp_f32_e32 v32, v32
	v_exp_f32_e32 v33, v33
	v_exp_f32_e32 v34, v34
	v_exp_f32_e32 v35, v35
	v_sub_f32_e32 v44, 1.0, v44
	v_sub_f32_e32 v45, 1.0, v45
	v_sub_f32_e32 v46, 1.0, v46
	v_sub_f32_e32 v47, 1.0, v47
	v_add_f32_e32 v32, 1.0, v32
	v_add_f32_e32 v33, 1.0, v33
	v_add_f32_e32 v34, 1.0, v34
	v_add_f32_e32 v35, 1.0, v35
	v_max_f32_e32 v44, 0, v44
	v_max_f32_e32 v45, 0, v45
	v_max_f32_e32 v46, 0, v46
	v_max_f32_e32 v47, 0, v47
	v_rcp_f32_e32 v32, v32
	v_rcp_f32_e32 v33, v33
	v_rcp_f32_e32 v34, v34
	v_rcp_f32_e32 v35, v35
	v_sqrt_f32_e32 v44, v44
	v_sqrt_f32_e32 v45, v45
	v_sqrt_f32_e32 v46, v46
	v_sqrt_f32_e32 v47, v47
	v_mul_f32_e32 v32, v32, v44
	v_mul_f32_e32 v33, v33, v45
	v_mul_f32_e32 v34, v34, v46
	v_mul_f32_e32 v35, v35, v47
	v_add_f32_e32 v28, v28, v52
	v_add_f32_e32 v29, v29, v53
	v_add_f32_e32 v30, v30, v54
	v_add_f32_e32 v31, v31, v55
	v_mul_f32_e32 v28, 0xbfb8aa3b, v28
	v_mul_f32_e32 v29, 0xbfb8aa3b, v29
	v_mul_f32_e32 v30, 0xbfb8aa3b, v30
	v_mul_f32_e32 v31, 0xbfb8aa3b, v31
	v_exp_f32_e32 v28, v28
	v_exp_f32_e32 v29, v29
	v_exp_f32_e32 v30, v30
	v_exp_f32_e32 v31, v31
	v_add_f32_e32 v28, 1.0, v28
	v_add_f32_e32 v29, 1.0, v29
	v_add_f32_e32 v30, 1.0, v30
	v_add_f32_e32 v31, 1.0, v31
	v_rcp_f32_e32 v28, v28
	v_rcp_f32_e32 v29, v29
	v_rcp_f32_e32 v30, v30
	v_rcp_f32_e32 v31, v31
	v_mul_f32_e32 v28, v72, v28
	v_mul_f32_e32 v29, v73, v29
	v_mul_f32_e32 v30, v74, v30
	v_mul_f32_e32 v31, v75, v31
	v_add_f32_e32 v24, v24, v48
	v_add_f32_e32 v25, v25, v49
	v_add_f32_e32 v26, v26, v50
	v_add_f32_e32 v27, v27, v51
	v_mul_f32_e32 v24, 0xbfb8aa3b, v24
	v_mul_f32_e32 v25, 0xbfb8aa3b, v25
	v_mul_f32_e32 v26, 0xbfb8aa3b, v26
	v_mul_f32_e32 v27, 0xbfb8aa3b, v27
	v_exp_f32_e32 v24, v24
	s_waitcnt vmcnt(1)
	v_mov_b64_e32 v[40:41], v[242:243]
	v_lshlrev_b32_e32 v42, 16, v40
	v_and_b32_e32 v40, 0xffff0000, v40
	v_lshlrev_b32_e32 v43, 16, v41
	v_and_b32_e32 v41, 0xffff0000, v41
	v_mul_f32_e32 v32, v32, v42
	v_mul_f32_e32 v33, v33, v40
	v_mul_f32_e32 v34, v34, v43
	v_mul_f32_e32 v35, v35, v41
	v_cvt_pk_bf16_f32 v32, v36, v32
	v_cvt_pk_bf16_f32 v33, v37, v33
	v_cvt_pk_bf16_f32 v34, v38, v34
	v_cvt_pk_bf16_f32 v35, v39, v35
	global_load_dwordx2 v[240:241], v[98:99], off offset:32
	global_store_dwordx4 v[96:97], v[32:35], off offset:64
	v_add_f32_e32 v36, v28, v28
	v_add_f32_e32 v37, v29, v29
	v_add_f32_e32 v38, v30, v30
	v_add_f32_e32 v39, v31, v31
	v_exp_f32_e32 v36, v36
	v_exp_f32_e32 v37, v37
	v_exp_f32_e32 v38, v38
	v_exp_f32_e32 v39, v39
	v_exp_f32_e32 v25, v25
	v_exp_f32_e32 v26, v26
	v_exp_f32_e32 v27, v27
	v_sub_f32_e32 v36, 1.0, v36
	v_sub_f32_e32 v37, 1.0, v37
	v_sub_f32_e32 v38, 1.0, v38
	v_sub_f32_e32 v39, 1.0, v39
	v_add_f32_e32 v24, 1.0, v24
	v_add_f32_e32 v25, 1.0, v25
	v_add_f32_e32 v26, 1.0, v26
	v_add_f32_e32 v27, 1.0, v27
	v_max_f32_e32 v36, 0, v36
	v_max_f32_e32 v37, 0, v37
	v_max_f32_e32 v38, 0, v38
	v_max_f32_e32 v39, 0, v39
	v_rcp_f32_e32 v24, v24
	v_rcp_f32_e32 v25, v25
	v_rcp_f32_e32 v26, v26
	v_rcp_f32_e32 v27, v27
	v_sqrt_f32_e32 v36, v36
	v_sqrt_f32_e32 v37, v37
	v_sqrt_f32_e32 v38, v38
	v_sqrt_f32_e32 v39, v39
	v_mul_f32_e32 v24, v24, v36
	v_mul_f32_e32 v25, v25, v37
	v_mul_f32_e32 v26, v26, v38
	v_mul_f32_e32 v27, v27, v39
	v_add_f32_e32 v20, v20, v52
	v_add_f32_e32 v21, v21, v53
	v_add_f32_e32 v22, v22, v54
	v_add_f32_e32 v23, v23, v55
	v_mul_f32_e32 v20, 0xbfb8aa3b, v20
	v_mul_f32_e32 v21, 0xbfb8aa3b, v21
	v_mul_f32_e32 v22, 0xbfb8aa3b, v22
	v_mul_f32_e32 v23, 0xbfb8aa3b, v23
	v_exp_f32_e32 v20, v20
	v_exp_f32_e32 v21, v21
	v_exp_f32_e32 v22, v22
	v_exp_f32_e32 v23, v23
	v_add_f32_e32 v20, 1.0, v20
	v_add_f32_e32 v21, 1.0, v21
	v_add_f32_e32 v22, 1.0, v22
	v_add_f32_e32 v23, 1.0, v23
	v_rcp_f32_e32 v20, v20
	v_rcp_f32_e32 v21, v21
	v_rcp_f32_e32 v22, v22
	v_rcp_f32_e32 v23, v23
	v_mul_f32_e32 v20, v72, v20
	v_mul_f32_e32 v21, v73, v21
	v_mul_f32_e32 v22, v74, v22
	v_mul_f32_e32 v23, v75, v23
	v_add_f32_e32 v16, v16, v48
	v_add_f32_e32 v17, v17, v49
	v_add_f32_e32 v18, v18, v50
	v_add_f32_e32 v19, v19, v51
	v_mul_f32_e32 v16, 0xbfb8aa3b, v16
	v_mul_f32_e32 v17, 0xbfb8aa3b, v17
	v_mul_f32_e32 v18, 0xbfb8aa3b, v18
	v_mul_f32_e32 v19, 0xbfb8aa3b, v19
	v_exp_f32_e32 v16, v16
	v_exp_f32_e32 v17, v17
	v_exp_f32_e32 v18, v18
	v_exp_f32_e32 v19, v19
	v_add_f32_e32 v16, 1.0, v16
	v_add_f32_e32 v17, 1.0, v17
	v_add_f32_e32 v18, 1.0, v18
	v_add_f32_e32 v19, 1.0, v19
	v_rcp_f32_e32 v16, v16
	v_rcp_f32_e32 v17, v17
	v_rcp_f32_e32 v18, v18
	v_rcp_f32_e32 v19, v19
	s_waitcnt vmcnt(1)
	v_mov_b64_e32 v[32:33], v[240:241]
	v_lshlrev_b32_e32 v34, 16, v32
	v_and_b32_e32 v32, 0xffff0000, v32
	v_lshlrev_b32_e32 v35, 16, v33
	v_and_b32_e32 v33, 0xffff0000, v33
	v_mul_f32_e32 v24, v24, v34
	v_mul_f32_e32 v25, v25, v32
	v_mul_f32_e32 v26, v26, v35
	v_mul_f32_e32 v27, v27, v33
	v_cvt_pk_bf16_f32 v24, v28, v24
	v_cvt_pk_bf16_f32 v25, v29, v25
	v_cvt_pk_bf16_f32 v26, v30, v26
	v_cvt_pk_bf16_f32 v27, v31, v27
	global_load_dwordx2 v[242:243], v[90:91], off offset:32
	global_store_dwordx4 v[88:89], v[24:27], off offset:64
	v_add_f32_e32 v28, v20, v20
	v_add_f32_e32 v29, v21, v21
	v_add_f32_e32 v30, v22, v22
	v_add_f32_e32 v31, v23, v23
	v_exp_f32_e32 v28, v28
	v_exp_f32_e32 v29, v29
	v_exp_f32_e32 v30, v30
	v_exp_f32_e32 v31, v31
	v_sub_f32_e32 v28, 1.0, v28
	v_sub_f32_e32 v29, 1.0, v29
	v_sub_f32_e32 v30, 1.0, v30
	v_sub_f32_e32 v31, 1.0, v31
	v_max_f32_e32 v28, 0, v28
	v_max_f32_e32 v29, 0, v29
	v_max_f32_e32 v30, 0, v30
	v_max_f32_e32 v31, 0, v31
	v_sqrt_f32_e32 v28, v28
	v_sqrt_f32_e32 v29, v29
	v_sqrt_f32_e32 v30, v30
	v_sqrt_f32_e32 v31, v31
	v_mul_f32_e32 v16, v16, v28
	v_mul_f32_e32 v17, v17, v29
	v_mul_f32_e32 v18, v18, v30
	v_mul_f32_e32 v19, v19, v31
	v_add_f32_e32 v12, v12, v52
	v_add_f32_e32 v13, v13, v53
	v_add_f32_e32 v14, v14, v54
	v_add_f32_e32 v15, v15, v55
	v_mul_f32_e32 v12, 0xbfb8aa3b, v12
	v_mul_f32_e32 v13, 0xbfb8aa3b, v13
	v_mul_f32_e32 v14, 0xbfb8aa3b, v14
	v_mul_f32_e32 v15, 0xbfb8aa3b, v15
	v_exp_f32_e32 v12, v12
	v_exp_f32_e32 v13, v13
	v_exp_f32_e32 v14, v14
	v_exp_f32_e32 v15, v15
	v_add_f32_e32 v12, 1.0, v12
	v_add_f32_e32 v13, 1.0, v13
	v_add_f32_e32 v14, 1.0, v14
	v_add_f32_e32 v15, 1.0, v15
	v_rcp_f32_e32 v12, v12
	v_rcp_f32_e32 v13, v13
	v_rcp_f32_e32 v14, v14
	v_rcp_f32_e32 v15, v15
	v_mul_f32_e32 v12, v72, v12
	v_mul_f32_e32 v13, v73, v13
	v_mul_f32_e32 v14, v74, v14
	v_mul_f32_e32 v15, v75, v15
	v_add_f32_e32 v8, v8, v48
	v_add_f32_e32 v9, v9, v49
	v_add_f32_e32 v10, v10, v50
	v_add_f32_e32 v11, v11, v51
	v_mul_f32_e32 v8, 0xbfb8aa3b, v8
	v_mul_f32_e32 v9, 0xbfb8aa3b, v9
	v_mul_f32_e32 v10, 0xbfb8aa3b, v10
	v_mul_f32_e32 v11, 0xbfb8aa3b, v11
	v_exp_f32_e32 v8, v8
	v_exp_f32_e32 v9, v9
	v_exp_f32_e32 v10, v10
	v_exp_f32_e32 v11, v11
	v_add_f32_e32 v8, 1.0, v8
	v_add_f32_e32 v9, 1.0, v9
	v_add_f32_e32 v10, 1.0, v10
	v_add_f32_e32 v11, 1.0, v11
	v_rcp_f32_e32 v8, v8
	v_rcp_f32_e32 v9, v9
	v_rcp_f32_e32 v10, v10
	v_rcp_f32_e32 v11, v11
	v_add_f32_e32 v4, v4, v52
	v_add_f32_e32 v5, v5, v53
	v_add_f32_e32 v6, v6, v54
	v_add_f32_e32 v7, v7, v55
	v_mul_f32_e32 v4, 0xbfb8aa3b, v4
	v_mul_f32_e32 v5, 0xbfb8aa3b, v5
	v_mul_f32_e32 v6, 0xbfb8aa3b, v6
	v_mul_f32_e32 v7, 0xbfb8aa3b, v7
	v_exp_f32_e32 v4, v4
	v_exp_f32_e32 v5, v5
	v_exp_f32_e32 v6, v6
	s_waitcnt vmcnt(1)
	v_mov_b64_e32 v[24:25], v[242:243]
	v_lshlrev_b32_e32 v26, 16, v24
	v_and_b32_e32 v24, 0xffff0000, v24
	v_lshlrev_b32_e32 v27, 16, v25
	v_and_b32_e32 v25, 0xffff0000, v25
	v_mul_f32_e32 v16, v16, v26
	v_mul_f32_e32 v17, v17, v24
	v_mul_f32_e32 v18, v18, v27
	v_mul_f32_e32 v19, v19, v25
	v_cvt_pk_bf16_f32 v16, v20, v16
	v_cvt_pk_bf16_f32 v17, v21, v17
	v_cvt_pk_bf16_f32 v18, v22, v18
	v_cvt_pk_bf16_f32 v19, v23, v19
	global_load_dwordx2 v[240:241], v[84:85], off offset:32
	global_store_dwordx4 v[82:83], v[16:19], off offset:64
	v_add_f32_e32 v20, v12, v12
	v_add_f32_e32 v21, v13, v13
	v_add_f32_e32 v22, v14, v14
	v_add_f32_e32 v23, v15, v15
	v_exp_f32_e32 v20, v20
	v_exp_f32_e32 v21, v21
	v_exp_f32_e32 v22, v22
	v_exp_f32_e32 v23, v23
	v_sub_f32_e32 v20, 1.0, v20
	v_sub_f32_e32 v21, 1.0, v21
	v_sub_f32_e32 v22, 1.0, v22
	v_sub_f32_e32 v23, 1.0, v23
	v_max_f32_e32 v20, 0, v20
	v_max_f32_e32 v21, 0, v21
	v_max_f32_e32 v22, 0, v22
	v_max_f32_e32 v23, 0, v23
	v_sqrt_f32_e32 v20, v20
	v_sqrt_f32_e32 v21, v21
	v_sqrt_f32_e32 v22, v22
	v_sqrt_f32_e32 v23, v23
	v_mul_f32_e32 v8, v8, v20
	v_mul_f32_e32 v9, v9, v21
	v_mul_f32_e32 v10, v10, v22
	v_mul_f32_e32 v11, v11, v23
	v_exp_f32_e32 v7, v7
	v_add_f32_e32 v4, 1.0, v4
	v_add_f32_e32 v5, 1.0, v5
	v_add_f32_e32 v6, 1.0, v6
	v_add_f32_e32 v7, 1.0, v7
	v_rcp_f32_e32 v4, v4
	v_rcp_f32_e32 v5, v5
	v_rcp_f32_e32 v6, v6
	v_rcp_f32_e32 v7, v7
	v_mul_f32_e32 v4, v72, v4
	v_mul_f32_e32 v5, v73, v5
	v_mul_f32_e32 v6, v74, v6
	v_mul_f32_e32 v7, v75, v7
	v_add_f32_e32 v0, v0, v48
	v_add_f32_e32 v1, v1, v49
	v_add_f32_e32 v2, v2, v50
	v_add_f32_e32 v3, v3, v51
	v_mul_f32_e32 v0, 0xbfb8aa3b, v0
	v_mul_f32_e32 v1, 0xbfb8aa3b, v1
	v_mul_f32_e32 v2, 0xbfb8aa3b, v2
	v_mul_f32_e32 v3, 0xbfb8aa3b, v3
	v_exp_f32_e32 v0, v0
	v_exp_f32_e32 v1, v1
	v_exp_f32_e32 v2, v2
	v_exp_f32_e32 v3, v3
	v_add_f32_e32 v0, 1.0, v0
	v_add_f32_e32 v1, 1.0, v1
	v_add_f32_e32 v2, 1.0, v2
	v_add_f32_e32 v3, 1.0, v3
	v_rcp_f32_e32 v0, v0
	v_rcp_f32_e32 v1, v1
	v_rcp_f32_e32 v2, v2
	v_rcp_f32_e32 v3, v3
	s_waitcnt vmcnt(1)
	v_mov_b64_e32 v[16:17], v[240:241]
	v_lshlrev_b32_e32 v18, 16, v16
	v_and_b32_e32 v16, 0xffff0000, v16
	v_lshlrev_b32_e32 v19, 16, v17
	v_and_b32_e32 v17, 0xffff0000, v17
	v_mul_f32_e32 v8, v8, v18
	v_mul_f32_e32 v9, v9, v16
	v_mul_f32_e32 v10, v10, v19
	v_mul_f32_e32 v11, v11, v17
	v_cvt_pk_bf16_f32 v8, v12, v8
	v_cvt_pk_bf16_f32 v9, v13, v9
	v_cvt_pk_bf16_f32 v10, v14, v10
	v_cvt_pk_bf16_f32 v11, v15, v11
	global_load_dwordx2 v[242:243], v[80:81], off offset:32
	global_store_dwordx4 v[78:79], v[8:11], off offset:64
	v_add_f32_e32 v12, v4, v4
	v_add_f32_e32 v13, v5, v5
	v_add_f32_e32 v14, v6, v6
	v_add_f32_e32 v15, v7, v7
	v_exp_f32_e32 v12, v12
	v_exp_f32_e32 v13, v13
	v_exp_f32_e32 v14, v14
	v_exp_f32_e32 v15, v15
	v_sub_f32_e32 v12, 1.0, v12
	v_sub_f32_e32 v13, 1.0, v13
	v_sub_f32_e32 v14, 1.0, v14
	v_sub_f32_e32 v15, 1.0, v15
	v_max_f32_e32 v12, 0, v12
	v_max_f32_e32 v13, 0, v13
	v_max_f32_e32 v14, 0, v14
	v_max_f32_e32 v15, 0, v15
	v_sqrt_f32_e32 v12, v12
	v_sqrt_f32_e32 v13, v13
	v_sqrt_f32_e32 v14, v14
	v_sqrt_f32_e32 v15, v15
	v_mul_f32_e32 v0, v0, v12
	v_mul_f32_e32 v1, v1, v13
	v_mul_f32_e32 v2, v2, v14
	v_mul_f32_e32 v3, v3, v15
	s_waitcnt vmcnt(1)
	v_mov_b64_e32 v[8:9], v[242:243]
	v_lshlrev_b32_e32 v10, 16, v8
	v_and_b32_e32 v8, 0xffff0000, v8
	v_lshlrev_b32_e32 v11, 16, v9
	v_and_b32_e32 v9, 0xffff0000, v9
	v_mul_f32_e32 v0, v0, v10
	v_mul_f32_e32 v1, v1, v8
	v_mul_f32_e32 v2, v2, v11
	v_mul_f32_e32 v3, v3, v9
	v_cvt_pk_bf16_f32 v0, v4, v0
	v_cvt_pk_bf16_f32 v1, v5, v1
	v_cvt_pk_bf16_f32 v2, v6, v2
	v_cvt_pk_bf16_f32 v3, v7, v3
	global_store_dwordx4 v[76:77], v[0:3], off offset:64
	s_cbranch_vccnz .LBB0_406
